# GEMM K-loops: early post-MMA barrier on all 8 phases; loop-top SALU block moved behind the phase-1 LDS reads and DMA issue
# baseline (speedup 1.0000x reference)
; #define PG8_STAGE(bufoff, gbase, voff) do { _Pragma("unroll") for (int _i = 0; _i < 2; ++_i) \
;         __builtin_amdgcn_global_load_lds((const unsigned*)((const char*)(gbase) + (voff)[_i]), (LAS unsigned*)(lds + (bufoff) + ldsw + _i * 8192), 16, 0, 0); } while (0)
; #define PG8_LDA(dst, b, h) do { _Pragma("unroll") for (int m = 0; m < 4; ++m) _Pragma("unroll") for (int k = 0; k < 2; ++k) dst[m][k] = *(const LAS bf16x8*)(lds + PG8_SA(b, h) + aoff + m * 2048 + k * 1024); } while (0)
; #define PG8_LDB(dst, b, h) do { _Pragma("unroll") for (int n = 0; n < 2; ++n) _Pragma("unroll") for (int k = 0; k < 2; ++k) dst[n][k] = *(const LAS bf16x8*)(lds + PG8_SB(b, h) + boff + n * 2048 + k * 1024); } while (0)
; #define PG8_MMA(ai, bj, At, Bt) do { __builtin_amdgcn_s_setprio(1); _Pragma("unroll") for (int m = 0; m < 4; ++m) _Pragma("unroll") for (int n = 0; n < 2; ++n) _Pragma("unroll") for (int k = 0; k < 2; ++k) \
;         acc[ai][bj][m][n] = __builtin_amdgcn_mfma_f32_16x16x32_bf16(Bt[n][k], At[m][k], acc[ai][bj][m][n], 0, 0, 0); __builtin_amdgcn_s_setprio(0); } while (0)
; #define PG8_WAIT_V(n) asm volatile("s_waitcnt vmcnt(" #n ")" ::: "memory")
; #define PG8_WAIT_L(n) asm volatile("s_waitcnt lgkmcnt(" #n ")" ::: "memory")
; #define PG8_BAR __builtin_amdgcn_s_barrier()
; template <class Epi, class Sched, int LD>
; __device__ __forceinline__ void gemm_phase(LAS unsigned char* lds, const Gemm g, const Sched& S, const Epi& E) {
;     ...
;             const bool last = (t == nt - 2);
;             const char* a1 = cA + (size_t)(t + 1) * kstep;
;             const char* a2 = last ? nA : cA + (size_t)(t + 2) * kstep; const char* b2 = last ? nB : cB + (size_t)(t + 2) * kstep;
;             const char* a3 = a2 + kstep; const char* b3 = b2 + kstep;
;             PG8_LDB(B0, 0, 0); PG8_SCHED; PG8_LDA(At, 0, 0); PG8_STAGE(PG8_SA(1, 1), a1 + hstep, voffA);
;             PG8_WAIT_L(8); PG8_BAR; PG8_WAIT_L(0); PG8_MMA(0, 0, At, B0); PG8_BAR; PG8_SCHED;
;             PG8_LDB(B1, 0, 1); PG8_STAGE(PG8_SB(0, 0), b2, voffB);
;             PG8_BAR; PG8_WAIT_L(0); PG8_MMA(0, 1, At, B1); PG8_BAR;
;             PG8_LDA(At, 0, 1); PG8_STAGE(PG8_SA(0, 0), a2, voffA);
;             PG8_BAR; PG8_WAIT_L(0); PG8_MMA(1, 0, At, B0); PG8_BAR; PG8_SCHED;
;             PG8_STAGE(PG8_SB(0, 1), b2 + hstep, voffB);
;             PG8_WAIT_V(6); PG8_BAR; PG8_MMA(1, 1, At, B1); PG8_BAR;
.LBB0_58:
	ds_read_b128 v[140:143], v228
	ds_read_b128 v[150:153], v228 offset:1024
	ds_read_b128 v[154:157], v228 offset:2048
	ds_read_b128 v[176:179], v228 offset:3072
	s_add_i32 m0, s39, 0xc000
	ds_read_b128 v[180:183], v148
	ds_read_b128 v[184:187], v148 offset:1024
	ds_read_b128 v[188:191], v148 offset:2048
	ds_read_b128 v[192:195], v148 offset:3072
	ds_read_b128 v[196:199], v148 offset:4096
	ds_read_b128 v[200:203], v148 offset:5120
	ds_read_b128 v[204:207], v148 offset:6144
	ds_read_b128 v[208:211], v148 offset:7168
	global_load_lds_dwordx4 v132, s[46:47]
	s_add_i32 m0, s39, 0xe000
	s_nop 0
	global_load_lds_dwordx4 v138, s[46:47]
	s_add_i32 s71, s4, 2
	s_add_u32 s48, s46, 0x4000
	s_addc_u32 s5, s47, 0
	s_cmp_eq_u32 s68, s4
	s_cselect_b32 s4, s42, s48
	s_cselect_b32 s5, s43, s5
	s_cselect_b32 s48, s44, s69
	s_cselect_b32 s49, s45, s70
	s_add_u32 s50, s4, 0x8000
	s_addc_u32 s51, s5, 0
	s_add_i32 s72, 0, 0x10000
	s_waitcnt lgkmcnt(8)
	s_barrier
	s_waitcnt lgkmcnt(0)
	s_setprio 1
	v_mfma_f32_16x16x32_bf16 v[128:131], v[140:143], v[180:183], v[128:131]
	v_mfma_f32_16x16x32_bf16 v[124:127], v[154:157], v[180:183], v[124:127]
	v_mfma_f32_16x16x32_bf16 v[112:115], v[140:143], v[188:191], v[112:115]
	v_mfma_f32_16x16x32_bf16 v[108:111], v[154:157], v[188:191], v[108:111]
	v_mfma_f32_16x16x32_bf16 v[96:99], v[140:143], v[196:199], v[96:99]
	v_mfma_f32_16x16x32_bf16 v[92:95], v[154:157], v[196:199], v[92:95]
	v_mfma_f32_16x16x32_bf16 v[80:83], v[140:143], v[204:207], v[80:83]
	v_mfma_f32_16x16x32_bf16 v[76:79], v[154:157], v[204:207], v[76:79]
	v_mfma_f32_16x16x32_bf16 v[128:131], v[150:153], v[184:187], v[128:131]
	v_mfma_f32_16x16x32_bf16 v[124:127], v[176:179], v[184:187], v[124:127]
	v_mfma_f32_16x16x32_bf16 v[112:115], v[150:153], v[192:195], v[112:115]
	v_mfma_f32_16x16x32_bf16 v[108:111], v[176:179], v[192:195], v[108:111]
	v_mfma_f32_16x16x32_bf16 v[96:99], v[150:153], v[200:203], v[96:99]
	v_mfma_f32_16x16x32_bf16 v[92:95], v[176:179], v[200:203], v[92:95]
	s_setprio 2
	s_barrier
	v_mfma_f32_16x16x32_bf16 v[80:83], v[150:153], v[208:211], v[80:83]
	v_mfma_f32_16x16x32_bf16 v[76:79], v[176:179], v[208:211], v[76:79]
	s_setprio 0
	s_add_i32 s74, 0, 0x14000
	s_add_i32 s72, s72, s29
	ds_read_b128 v[212:215], v228 offset:16384
	ds_read_b128 v[216:219], v228 offset:17408
	ds_read_b128 v[220:223], v228 offset:18432
	ds_read_b128 v[224:227], v228 offset:19456
	s_mov_b32 m0, s72
	s_nop 0
	global_load_lds_dwordx4 v132, s[48:49]
	s_add_i32 m0, s72, 0x2000
	s_nop 0
	global_load_lds_dwordx4 v138, s[48:49]
	s_barrier
	s_waitcnt lgkmcnt(0)
	s_setprio 1
	v_mfma_f32_16x16x32_bf16 v[120:123], v[212:215], v[180:183], v[120:123]
	v_mfma_f32_16x16x32_bf16 v[116:119], v[220:223], v[180:183], v[116:119]
	v_mfma_f32_16x16x32_bf16 v[104:107], v[212:215], v[188:191], v[104:107]
	v_mfma_f32_16x16x32_bf16 v[100:103], v[220:223], v[188:191], v[100:103]
	v_mfma_f32_16x16x32_bf16 v[88:91], v[212:215], v[196:199], v[88:91]
	v_mfma_f32_16x16x32_bf16 v[84:87], v[220:223], v[196:199], v[84:87]
	v_mfma_f32_16x16x32_bf16 v[72:75], v[212:215], v[204:207], v[72:75]
	v_mfma_f32_16x16x32_bf16 v[68:71], v[220:223], v[204:207], v[68:71]
	v_mfma_f32_16x16x32_bf16 v[120:123], v[216:219], v[184:187], v[120:123]
	v_mfma_f32_16x16x32_bf16 v[116:119], v[224:227], v[184:187], v[116:119]
	v_mfma_f32_16x16x32_bf16 v[104:107], v[216:219], v[192:195], v[104:107]
	v_mfma_f32_16x16x32_bf16 v[100:103], v[224:227], v[192:195], v[100:103]
	v_mfma_f32_16x16x32_bf16 v[88:91], v[216:219], v[200:203], v[88:91]
	v_mfma_f32_16x16x32_bf16 v[84:87], v[224:227], v[200:203], v[84:87]
	s_setprio 2
	s_mov_b32 m0, s39
	s_barrier
	v_mfma_f32_16x16x32_bf16 v[72:75], v[216:219], v[208:211], v[72:75]
	v_mfma_f32_16x16x32_bf16 v[68:71], v[224:227], v[208:211], v[68:71]
	s_setprio 0
	ds_read_b128 v[180:183], v148 offset:16384
	ds_read_b128 v[184:187], v148 offset:17408
	ds_read_b128 v[188:191], v148 offset:18432
	ds_read_b128 v[192:195], v148 offset:19456
	ds_read_b128 v[196:199], v148 offset:20480
	ds_read_b128 v[200:203], v148 offset:21504
	ds_read_b128 v[204:207], v148 offset:22528
	ds_read_b128 v[208:211], v148 offset:23552
	global_load_lds_dwordx4 v132, s[4:5]
	s_mov_b32 m0, s52
	s_nop 0
	global_load_lds_dwordx4 v138, s[4:5]
	s_barrier
	s_waitcnt lgkmcnt(0)
	s_setprio 1
	v_mfma_f32_16x16x32_bf16 v[64:67], v[140:143], v[180:183], v[64:67]
	v_mfma_f32_16x16x32_bf16 v[60:63], v[154:157], v[180:183], v[60:63]
	v_mfma_f32_16x16x32_bf16 v[48:51], v[140:143], v[188:191], v[48:51]
	v_mfma_f32_16x16x32_bf16 v[44:47], v[154:157], v[188:191], v[44:47]
	v_mfma_f32_16x16x32_bf16 v[32:35], v[140:143], v[196:199], v[32:35]
	v_mfma_f32_16x16x32_bf16 v[28:31], v[154:157], v[196:199], v[28:31]
	v_mfma_f32_16x16x32_bf16 v[16:19], v[140:143], v[204:207], v[16:19]
	v_mfma_f32_16x16x32_bf16 v[12:15], v[154:157], v[204:207], v[12:15]
	v_mfma_f32_16x16x32_bf16 v[64:67], v[150:153], v[184:187], v[64:67]
	v_mfma_f32_16x16x32_bf16 v[60:63], v[176:179], v[184:187], v[60:63]
	v_mfma_f32_16x16x32_bf16 v[48:51], v[150:153], v[192:195], v[48:51]
	v_mfma_f32_16x16x32_bf16 v[44:47], v[176:179], v[192:195], v[44:47]
	v_mfma_f32_16x16x32_bf16 v[32:35], v[150:153], v[200:203], v[32:35]
	v_mfma_f32_16x16x32_bf16 v[28:31], v[176:179], v[200:203], v[28:31]
	s_setprio 2
	s_barrier
	v_mfma_f32_16x16x32_bf16 v[16:19], v[150:153], v[208:211], v[16:19]
	v_mfma_f32_16x16x32_bf16 v[12:15], v[176:179], v[208:211], v[12:15]
	s_setprio 0
	s_add_u32 s72, s48, 0x4000
	s_addc_u32 s73, s49, 0
	s_add_i32 s74, s74, s29
	s_mov_b32 m0, s74
	s_nop 0
	global_load_lds_dwordx4 v132, s[72:73]
	s_add_i32 m0, s74, 0x2000
	s_nop 0
	global_load_lds_dwordx4 v138, s[72:73]
	s_waitcnt vmcnt(6)
	s_barrier
; #define PG8_STAGE(bufoff, gbase, voff) do { _Pragma("unroll") for (int _i = 0; _i < 2; ++_i) \
;         __builtin_amdgcn_global_load_lds((const unsigned*)((const char*)(gbase) + (voff)[_i]), (LAS unsigned*)(lds + (bufoff) + ldsw + _i * 8192), 16, 0, 0); } while (0)
; #define PG8_LDA(dst, b, h) do { _Pragma("unroll") for (int m = 0; m < 4; ++m) _Pragma("unroll") for (int k = 0; k < 2; ++k) dst[m][k] = *(const LAS bf16x8*)(lds + PG8_SA(b, h) + aoff + m * 2048 + k * 1024); } while (0)
; #define PG8_LDB(dst, b, h) do { _Pragma("unroll") for (int n = 0; n < 2; ++n) _Pragma("unroll") for (int k = 0; k < 2; ++k) dst[n][k] = *(const LAS bf16x8*)(lds + PG8_SB(b, h) + boff + n * 2048 + k * 1024); } while (0)
; #define PG8_MMA(ai, bj, At, Bt) do { __builtin_amdgcn_s_setprio(1); _Pragma("unroll") for (int m = 0; m < 4; ++m) _Pragma("unroll") for (int n = 0; n < 2; ++n) _Pragma("unroll") for (int k = 0; k < 2; ++k) \
;         acc[ai][bj][m][n] = __builtin_amdgcn_mfma_f32_16x16x32_bf16(Bt[n][k], At[m][k], acc[ai][bj][m][n], 0, 0, 0); __builtin_amdgcn_s_setprio(0); } while (0)
; #define PG8_WAIT_V(n) asm volatile("s_waitcnt vmcnt(" #n ")" ::: "memory")
; #define PG8_WAIT_L(n) asm volatile("s_waitcnt lgkmcnt(" #n ")" ::: "memory")
; #define PG8_BAR __builtin_amdgcn_s_barrier()
; #define PG8_SCHED __builtin_amdgcn_sched_barrier(0)
; template <class Epi, class Sched, int LD>
; __device__ __forceinline__ void gemm_phase(LAS unsigned char* lds, const Gemm g, const Sched& S, const Epi& E) {
;     ...
;             PG8_WAIT_V(6); PG8_BAR; PG8_MMA(1, 1, At, B1); PG8_BAR;
;             PG8_LDB(B0, 1, 0); PG8_SCHED; PG8_LDA(At, 1, 0); PG8_STAGE(PG8_SA(0, 1), a2 + hstep, voffA);
;             PG8_WAIT_L(8); PG8_BAR; PG8_WAIT_L(0); PG8_MMA(0, 0, At, B0); PG8_BAR; PG8_SCHED;
;             PG8_LDB(B1, 1, 1); PG8_STAGE(PG8_SB(1, 0), b3, voffB);
;             PG8_BAR; PG8_WAIT_L(0); PG8_MMA(0, 1, At, B1); PG8_BAR;
;             PG8_LDA(At, 1, 1); PG8_STAGE(PG8_SA(1, 0), a3, voffA);
	s_setprio 1
	v_mfma_f32_16x16x32_bf16 v[56:59], v[212:215], v[180:183], v[56:59]
	v_mfma_f32_16x16x32_bf16 v[52:55], v[220:223], v[180:183], v[52:55]
	v_mfma_f32_16x16x32_bf16 v[40:43], v[212:215], v[188:191], v[40:43]
	v_mfma_f32_16x16x32_bf16 v[36:39], v[220:223], v[188:191], v[36:39]
	v_mfma_f32_16x16x32_bf16 v[24:27], v[212:215], v[196:199], v[24:27]
	v_mfma_f32_16x16x32_bf16 v[20:23], v[220:223], v[196:199], v[20:23]
	v_mfma_f32_16x16x32_bf16 v[8:11], v[212:215], v[204:207], v[8:11]
	v_mfma_f32_16x16x32_bf16 v[4:7], v[220:223], v[204:207], v[4:7]
	v_mfma_f32_16x16x32_bf16 v[56:59], v[216:219], v[184:187], v[56:59]
	v_mfma_f32_16x16x32_bf16 v[52:55], v[224:227], v[184:187], v[52:55]
	v_mfma_f32_16x16x32_bf16 v[40:43], v[216:219], v[192:195], v[40:43]
	v_mfma_f32_16x16x32_bf16 v[36:39], v[224:227], v[192:195], v[36:39]
	v_mfma_f32_16x16x32_bf16 v[24:27], v[216:219], v[200:203], v[24:27]
	v_mfma_f32_16x16x32_bf16 v[20:23], v[224:227], v[200:203], v[20:23]
	s_setprio 2
	s_add_i32 s72, 0, 0x18000
	s_barrier
	v_mfma_f32_16x16x32_bf16 v[8:11], v[216:219], v[208:211], v[8:11]
	v_mfma_f32_16x16x32_bf16 v[4:7], v[224:227], v[208:211], v[4:7]
	s_setprio 0
	ds_read_b128 v[140:143], v228 offset:32768
	ds_read_b128 v[150:153], v228 offset:33792
	ds_read_b128 v[154:157], v228 offset:34816
	ds_read_b128 v[176:179], v228 offset:35840
	s_add_u32 s4, s4, 0x4000
	s_addc_u32 s5, s5, 0
	s_mov_b32 m0, s53
	ds_read_b128 v[180:183], v148 offset:32768
	ds_read_b128 v[184:187], v148 offset:33792
	ds_read_b128 v[188:191], v148 offset:34816
	ds_read_b128 v[192:195], v148 offset:35840
	ds_read_b128 v[196:199], v148 offset:36864
	ds_read_b128 v[200:203], v148 offset:37888
	ds_read_b128 v[204:207], v148 offset:38912
	ds_read_b128 v[208:211], v148 offset:39936
	global_load_lds_dwordx4 v132, s[4:5]
	s_mov_b32 m0, s54
	s_nop 0
	global_load_lds_dwordx4 v138, s[4:5]
	s_waitcnt lgkmcnt(8)
	s_barrier
	s_waitcnt lgkmcnt(0)
	s_setprio 1
	v_mfma_f32_16x16x32_bf16 v[128:131], v[140:143], v[180:183], v[128:131]
	v_mfma_f32_16x16x32_bf16 v[124:127], v[154:157], v[180:183], v[124:127]
	v_mfma_f32_16x16x32_bf16 v[112:115], v[140:143], v[188:191], v[112:115]
	v_mfma_f32_16x16x32_bf16 v[108:111], v[154:157], v[188:191], v[108:111]
	v_mfma_f32_16x16x32_bf16 v[96:99], v[140:143], v[196:199], v[96:99]
	v_mfma_f32_16x16x32_bf16 v[92:95], v[154:157], v[196:199], v[92:95]
	v_mfma_f32_16x16x32_bf16 v[80:83], v[140:143], v[204:207], v[80:83]
	v_mfma_f32_16x16x32_bf16 v[76:79], v[154:157], v[204:207], v[76:79]
	v_mfma_f32_16x16x32_bf16 v[128:131], v[150:153], v[184:187], v[128:131]
	v_mfma_f32_16x16x32_bf16 v[124:127], v[176:179], v[184:187], v[124:127]
	v_mfma_f32_16x16x32_bf16 v[112:115], v[150:153], v[192:195], v[112:115]
	v_mfma_f32_16x16x32_bf16 v[108:111], v[176:179], v[192:195], v[108:111]
	v_mfma_f32_16x16x32_bf16 v[96:99], v[150:153], v[200:203], v[96:99]
	v_mfma_f32_16x16x32_bf16 v[92:95], v[176:179], v[200:203], v[92:95]
	s_setprio 2
	s_barrier
	v_mfma_f32_16x16x32_bf16 v[80:83], v[150:153], v[208:211], v[80:83]
	v_mfma_f32_16x16x32_bf16 v[76:79], v[176:179], v[208:211], v[76:79]
	s_setprio 0
	s_add_i32 s73, 0, 0x1c000
	s_add_u32 s4, s48, 0x8000
	s_addc_u32 s5, s49, 0
	s_add_i32 s72, s72, s29
	ds_read_b128 v[212:215], v228 offset:49152
	ds_read_b128 v[216:219], v228 offset:50176
	ds_read_b128 v[220:223], v228 offset:51200
	ds_read_b128 v[224:227], v228 offset:52224
	s_mov_b32 m0, s72
	s_nop 0
	global_load_lds_dwordx4 v132, s[4:5]
	s_add_i32 m0, s72, 0x2000
	s_nop 0
	global_load_lds_dwordx4 v138, s[4:5]
	s_barrier
	s_waitcnt lgkmcnt(0)
	s_setprio 1
	v_mfma_f32_16x16x32_bf16 v[120:123], v[212:215], v[180:183], v[120:123]
	v_mfma_f32_16x16x32_bf16 v[116:119], v[220:223], v[180:183], v[116:119]
	v_mfma_f32_16x16x32_bf16 v[104:107], v[212:215], v[188:191], v[104:107]
	v_mfma_f32_16x16x32_bf16 v[100:103], v[220:223], v[188:191], v[100:103]
	v_mfma_f32_16x16x32_bf16 v[88:91], v[212:215], v[196:199], v[88:91]
	v_mfma_f32_16x16x32_bf16 v[84:87], v[220:223], v[196:199], v[84:87]
	v_mfma_f32_16x16x32_bf16 v[72:75], v[212:215], v[204:207], v[72:75]
	v_mfma_f32_16x16x32_bf16 v[68:71], v[220:223], v[204:207], v[68:71]
	v_mfma_f32_16x16x32_bf16 v[120:123], v[216:219], v[184:187], v[120:123]
	v_mfma_f32_16x16x32_bf16 v[116:119], v[224:227], v[184:187], v[116:119]
	v_mfma_f32_16x16x32_bf16 v[104:107], v[216:219], v[192:195], v[104:107]
	v_mfma_f32_16x16x32_bf16 v[100:103], v[224:227], v[192:195], v[100:103]
	v_mfma_f32_16x16x32_bf16 v[88:91], v[216:219], v[200:203], v[88:91]
	v_mfma_f32_16x16x32_bf16 v[84:87], v[224:227], v[200:203], v[84:87]
	s_setprio 2
	s_mov_b32 m0, s55
	s_barrier
	v_mfma_f32_16x16x32_bf16 v[72:75], v[216:219], v[208:211], v[72:75]
	v_mfma_f32_16x16x32_bf16 v[68:71], v[224:227], v[208:211], v[68:71]
	s_setprio 0
	ds_read_b128 v[180:183], v148 offset:49152
	ds_read_b128 v[184:187], v148 offset:50176
	ds_read_b128 v[188:191], v148 offset:51200
	ds_read_b128 v[192:195], v148 offset:52224
	ds_read_b128 v[196:199], v148 offset:53248
	ds_read_b128 v[200:203], v148 offset:54272
	ds_read_b128 v[204:207], v148 offset:55296
	ds_read_b128 v[208:211], v148 offset:56320
	global_load_lds_dwordx4 v132, s[50:51]
	s_mov_b32 m0, s56
	s_nop 0
	global_load_lds_dwordx4 v138, s[50:51]
	s_barrier
; #define PG8_STAGE(bufoff, gbase, voff) do { _Pragma("unroll") for (int _i = 0; _i < 2; ++_i) \
;         __builtin_amdgcn_global_load_lds((const unsigned*)((const char*)(gbase) + (voff)[_i]), (LAS unsigned*)(lds + (bufoff) + ldsw + _i * 8192), 16, 0, 0); } while (0)
; #define PG8_MMA(ai, bj, At, Bt) do { __builtin_amdgcn_s_setprio(1); _Pragma("unroll") for (int m = 0; m < 4; ++m) _Pragma("unroll") for (int n = 0; n < 2; ++n) _Pragma("unroll") for (int k = 0; k < 2; ++k) \
;         acc[ai][bj][m][n] = __builtin_amdgcn_mfma_f32_16x16x32_bf16(Bt[n][k], At[m][k], acc[ai][bj][m][n], 0, 0, 0); __builtin_amdgcn_s_setprio(0); } while (0)
; #define PG8_WAIT_V(n) asm volatile("s_waitcnt vmcnt(" #n ")" ::: "memory")
; #define PG8_WAIT_L(n) asm volatile("s_waitcnt lgkmcnt(" #n ")" ::: "memory")
; #define PG8_BAR __builtin_amdgcn_s_barrier()
; #define PG8_SCHED __builtin_amdgcn_sched_barrier(0)
;     __device__ __forceinline__ void operator()(const f32x4 (&acc)[2][2][4][2], const Unit& u, int wr, int wc, int fr, int fq) const {
;     ...
;         } else {
;             float* base = PART + (size_t)u.part * (512 * 2048);
; #pragma unroll
;             for (int ai = 0; ai < 2; ++ai)
; #pragma unroll
;                 for (int m = 0; m < 4; ++m) {
;                     float* rowp = base + (size_t)(row0 - 8192 + ai * HALF + m * 16) * D_MODEL + col0;
; #pragma unroll
;                     for (int bj = 0; bj < 2; ++bj)
; #pragma unroll
;                         for (int n = 0; n < 2; ++n) *(f32x4*)(rowp + bj * HALF + n * 16) = acc[ai][bj][m][n];
;                 }
; template <class Epi, class Sched, int LD>
; __device__ __forceinline__ void gemm_phase(LAS unsigned char* lds, const Gemm g, const Sched& S, const Epi& E) {
;     ...
;             PG8_BAR; PG8_WAIT_L(0); PG8_MMA(1, 0, At, B0); PG8_BAR; PG8_SCHED;
;             PG8_STAGE(PG8_SB(1, 1), b3 + hstep, voffB);
;             PG8_WAIT_V(6); PG8_BAR; PG8_MMA(1, 1, At, B1); PG8_BAR;
	s_waitcnt lgkmcnt(0)
	s_setprio 1
	v_mfma_f32_16x16x32_bf16 v[64:67], v[140:143], v[180:183], v[64:67]
	v_mfma_f32_16x16x32_bf16 v[60:63], v[154:157], v[180:183], v[60:63]
	v_mfma_f32_16x16x32_bf16 v[48:51], v[140:143], v[188:191], v[48:51]
	v_mfma_f32_16x16x32_bf16 v[44:47], v[154:157], v[188:191], v[44:47]
	v_mfma_f32_16x16x32_bf16 v[32:35], v[140:143], v[196:199], v[32:35]
	v_mfma_f32_16x16x32_bf16 v[28:31], v[154:157], v[196:199], v[28:31]
	v_mfma_f32_16x16x32_bf16 v[16:19], v[140:143], v[204:207], v[16:19]
	v_mfma_f32_16x16x32_bf16 v[12:15], v[154:157], v[204:207], v[12:15]
	v_mfma_f32_16x16x32_bf16 v[64:67], v[150:153], v[184:187], v[64:67]
	v_mfma_f32_16x16x32_bf16 v[60:63], v[176:179], v[184:187], v[60:63]
	v_mfma_f32_16x16x32_bf16 v[48:51], v[150:153], v[192:195], v[48:51]
	v_mfma_f32_16x16x32_bf16 v[44:47], v[176:179], v[192:195], v[44:47]
	v_mfma_f32_16x16x32_bf16 v[32:35], v[150:153], v[200:203], v[32:35]
	v_mfma_f32_16x16x32_bf16 v[28:31], v[176:179], v[200:203], v[28:31]
	s_setprio 2
	s_barrier
	v_mfma_f32_16x16x32_bf16 v[16:19], v[150:153], v[208:211], v[16:19]
	v_mfma_f32_16x16x32_bf16 v[12:15], v[176:179], v[208:211], v[12:15]
	s_setprio 0
	s_add_u32 s4, s48, 0xc000
	s_addc_u32 s5, s49, 0
	s_add_i32 s48, s73, s29
	s_mov_b32 m0, s48
	s_nop 0
	global_load_lds_dwordx4 v132, s[4:5]
	s_add_i32 m0, s48, 0x2000
	s_nop 0
	global_load_lds_dwordx4 v138, s[4:5]
	s_waitcnt vmcnt(6)
	s_barrier
	s_setprio 1
	v_mfma_f32_16x16x32_bf16 v[56:59], v[212:215], v[180:183], v[56:59]
	v_mfma_f32_16x16x32_bf16 v[52:55], v[220:223], v[180:183], v[52:55]
	v_mfma_f32_16x16x32_bf16 v[40:43], v[212:215], v[188:191], v[40:43]
	v_mfma_f32_16x16x32_bf16 v[36:39], v[220:223], v[188:191], v[36:39]
	v_mfma_f32_16x16x32_bf16 v[24:27], v[212:215], v[196:199], v[24:27]
	v_mfma_f32_16x16x32_bf16 v[20:23], v[220:223], v[196:199], v[20:23]
	v_mfma_f32_16x16x32_bf16 v[8:11], v[212:215], v[204:207], v[8:11]
	v_mfma_f32_16x16x32_bf16 v[4:7], v[220:223], v[204:207], v[4:7]
	v_mfma_f32_16x16x32_bf16 v[56:59], v[216:219], v[184:187], v[56:59]
	v_mfma_f32_16x16x32_bf16 v[52:55], v[224:227], v[184:187], v[52:55]
	v_mfma_f32_16x16x32_bf16 v[40:43], v[216:219], v[192:195], v[40:43]
	v_mfma_f32_16x16x32_bf16 v[36:39], v[224:227], v[192:195], v[36:39]
	v_mfma_f32_16x16x32_bf16 v[24:27], v[216:219], v[200:203], v[24:27]
	v_mfma_f32_16x16x32_bf16 v[20:23], v[224:227], v[200:203], v[20:23]
	s_setprio 2
	s_add_u32 s46, s46, 0x10000
	s_addc_u32 s47, s47, 0
	s_add_u32 s69, s69, 0x10000
	s_addc_u32 s70, s70, 0
	s_cmp_ge_i32 s71, s65
	s_mov_b32 s4, s71
	s_barrier
	v_mfma_f32_16x16x32_bf16 v[8:11], v[216:219], v[208:211], v[8:11]
	v_mfma_f32_16x16x32_bf16 v[4:7], v[224:227], v[208:211], v[4:7]
	s_setprio 0
	s_cbranch_scc0 .LBB0_58
	v_lshl_add_u32 v142, s67, 8, v137
	v_lshl_or_b32 v140, s66, 8, v147
	s_mov_b64 s[4:5], -1
	s_cmp_gt_i32 s18, -1
	v_ashrrev_i32_e32 v141, 31, v140
	v_ashrrev_i32_e32 v143, 31, v142
	s_cbranch_scc0 .LBB0_61
	s_lshl_b64 s[4:5], s[18:19], 22
	v_readlane_b32 s18, v252, 10
	s_add_u32 s4, s18, s4
	v_readlane_b32 s18, v252, 11
	s_addc_u32 s5, s18, s5
	v_lshl_add_u64 v[144:145], v[140:141], 2, s[4:5]
	v_lshlrev_b64 v[150:151], 13, v[142:143]
	s_brev_b32 s4, 63
	v_lshl_add_u64 v[144:145], v[144:145], 0, v[150:151]
	s_mov_b32 s5, -1
	v_lshl_add_u64 v[150:151], v[144:145], 0, s[4:5]
	s_brev_b32 s4, 63
	v_add_co_u32_e32 v152, vcc, s4, v144
	s_mov_b32 s4, 0xfc020000
	s_nop 0
	v_addc_co_u32_e32 v153, vcc, -1, v145, vcc
	s_mov_b32 s5, -1
	global_store_dwordx4 v[152:153], v[128:131], off
	global_store_dwordx4 v[150:151], v[124:127], off offset:64
	global_store_dwordx4 v[150:151], v[120:123], off offset:512
	global_store_dwordx4 v[150:151], v[116:119], off offset:576
	v_lshl_add_u64 v[150:151], v[144:145], 0, s[4:5]
	s_mov_b32 s4, 0xfc020000
	v_add_co_u32_e32 v152, vcc, s4, v144
	s_mov_b32 s4, 0xfc040000
	s_nop 0
	v_addc_co_u32_e32 v153, vcc, -1, v145, vcc
	s_mov_b32 s5, -1
	global_store_dwordx4 v[152:153], v[112:115], off
	global_store_dwordx4 v[150:151], v[108:111], off offset:64
	global_store_dwordx4 v[150:151], v[104:107], off offset:512
	global_store_dwordx4 v[150:151], v[100:103], off offset:576
	v_lshl_add_u64 v[150:151], v[144:145], 0, s[4:5]
	s_mov_b32 s4, 0xfc040000
	v_add_co_u32_e32 v152, vcc, s4, v144
	s_mov_b32 s4, 0xfc060000
	s_nop 0
	v_addc_co_u32_e32 v153, vcc, -1, v145, vcc
	s_mov_b32 s5, -1
	global_store_dwordx4 v[152:153], v[96:99], off
	global_store_dwordx4 v[150:151], v[92:95], off offset:64
	global_store_dwordx4 v[150:151], v[88:91], off offset:512
	global_store_dwordx4 v[150:151], v[84:87], off offset:576
	v_lshl_add_u64 v[150:151], v[144:145], 0, s[4:5]
	s_mov_b32 s4, 0xfc060000
	v_add_co_u32_e32 v152, vcc, s4, v144
	s_mov_b32 s4, 0xfc100000
	s_nop 0
	v_addc_co_u32_e32 v153, vcc, -1, v145, vcc
	s_mov_b32 s5, -1
	global_store_dwordx4 v[152:153], v[80:83], off
	global_store_dwordx4 v[150:151], v[76:79], off offset:64
	global_store_dwordx4 v[150:151], v[72:75], off offset:512
	global_store_dwordx4 v[150:151], v[68:71], off offset:576
	v_lshl_add_u64 v[150:151], v[144:145], 0, s[4:5]
	s_mov_b32 s4, 0xfc100000
	v_add_co_u32_e32 v152, vcc, s4, v144
	s_mov_b32 s4, 0xfc120000
	s_nop 0
	v_addc_co_u32_e32 v153, vcc, -1, v145, vcc
	s_mov_b32 s5, -1
	global_store_dwordx4 v[152:153], v[64:67], off
	global_store_dwordx4 v[150:151], v[60:63], off offset:64
	global_store_dwordx4 v[150:151], v[56:59], off offset:512
	global_store_dwordx4 v[150:151], v[52:55], off offset:576
	v_lshl_add_u64 v[150:151], v[144:145], 0, s[4:5]
	s_mov_b32 s4, 0xfc120000
	v_add_co_u32_e32 v152, vcc, s4, v144
	s_mov_b32 s4, 0xfc140000
	s_nop 0
	v_addc_co_u32_e32 v153, vcc, -1, v145, vcc
	s_mov_b32 s5, -1
	global_store_dwordx4 v[152:153], v[48:51], off
	global_store_dwordx4 v[150:151], v[44:47], off offset:64
	global_store_dwordx4 v[150:151], v[40:43], off offset:512
	global_store_dwordx4 v[150:151], v[36:39], off offset:576
	v_lshl_add_u64 v[150:151], v[144:145], 0, s[4:5]
	s_mov_b32 s4, 0xfc140000
	v_add_co_u32_e32 v152, vcc, s4, v144
	s_mov_b32 s4, 0xfc160000
	s_nop 0
	v_addc_co_u32_e32 v153, vcc, -1, v145, vcc
	s_mov_b32 s5, -1
	global_store_dwordx4 v[152:153], v[32:35], off
	global_store_dwordx4 v[150:151], v[28:31], off offset:64
	global_store_dwordx4 v[150:151], v[24:27], off offset:512
	global_store_dwordx4 v[150:151], v[20:23], off offset:576
	v_lshl_add_u64 v[150:151], v[144:145], 0, s[4:5]
	v_add_co_u32_e32 v144, vcc, 0xfc160000, v144
	s_mov_b64 s[4:5], 0
	s_nop 0
	v_addc_co_u32_e32 v145, vcc, -1, v145, vcc
	global_store_dwordx4 v[144:145], v[16:19], off
	global_store_dwordx4 v[150:151], v[12:15], off offset:64
	global_store_dwordx4 v[150:151], v[8:11], off offset:512
	global_store_dwordx4 v[150:151], v[4:7], off offset:576

; #define PG8_STAGE(bufoff, gbase, voff) do { _Pragma("unroll") for (int _i = 0; _i < 2; ++_i) \
;         __builtin_amdgcn_global_load_lds((const unsigned*)((const char*)(gbase) + (voff)[_i]), (LAS unsigned*)(lds + (bufoff) + ldsw + _i * 8192), 16, 0, 0); } while (0)
; #define PG8_LDA(dst, b, h) do { _Pragma("unroll") for (int m = 0; m < 4; ++m) _Pragma("unroll") for (int k = 0; k < 2; ++k) dst[m][k] = *(const LAS bf16x8*)(lds + PG8_SA(b, h) + aoff + m * 2048 + k * 1024); } while (0)
; #define PG8_LDB(dst, b, h) do { _Pragma("unroll") for (int n = 0; n < 2; ++n) _Pragma("unroll") for (int k = 0; k < 2; ++k) dst[n][k] = *(const LAS bf16x8*)(lds + PG8_SB(b, h) + boff + n * 2048 + k * 1024); } while (0)
; #define PG8_MMA(ai, bj, At, Bt) do { __builtin_amdgcn_s_setprio(1); _Pragma("unroll") for (int m = 0; m < 4; ++m) _Pragma("unroll") for (int n = 0; n < 2; ++n) _Pragma("unroll") for (int k = 0; k < 2; ++k) \
;         acc[ai][bj][m][n] = __builtin_amdgcn_mfma_f32_16x16x32_bf16(Bt[n][k], At[m][k], acc[ai][bj][m][n], 0, 0, 0); __builtin_amdgcn_s_setprio(0); } while (0)
; #define PG8_WAIT_V(n) asm volatile("s_waitcnt vmcnt(" #n ")" ::: "memory")
; #define PG8_WAIT_L(n) asm volatile("s_waitcnt lgkmcnt(" #n ")" ::: "memory")
; #define PG8_BAR __builtin_amdgcn_s_barrier()
; template <class Epi, class Sched, int LD>
; __device__ __forceinline__ void gemm_phase(LAS unsigned char* lds, const Gemm g, const Sched& S, const Epi& E) {
;     ...
;             const bool last = (t == nt - 2);
;             const char* a1 = cA + (size_t)(t + 1) * kstep;
;             const char* a2 = last ? nA : cA + (size_t)(t + 2) * kstep; const char* b2 = last ? nB : cB + (size_t)(t + 2) * kstep;
;             const char* a3 = a2 + kstep; const char* b3 = b2 + kstep;
;             PG8_LDB(B0, 0, 0); PG8_SCHED; PG8_LDA(At, 0, 0); PG8_STAGE(PG8_SA(1, 1), a1 + hstep, voffA);
;             PG8_WAIT_L(8); PG8_BAR; PG8_WAIT_L(0); PG8_MMA(0, 0, At, B0); PG8_BAR; PG8_SCHED;
;             PG8_LDB(B1, 0, 1); PG8_STAGE(PG8_SB(0, 0), b2, voffB);
;             PG8_BAR; PG8_WAIT_L(0); PG8_MMA(0, 1, At, B1); PG8_BAR;
;             PG8_LDA(At, 0, 1); PG8_STAGE(PG8_SA(0, 0), a2, voffA);
;             PG8_BAR; PG8_WAIT_L(0); PG8_MMA(1, 0, At, B0); PG8_BAR; PG8_SCHED;
;             PG8_STAGE(PG8_SB(0, 1), b2 + hstep, voffB);
;             PG8_WAIT_V(6); PG8_BAR; PG8_MMA(1, 1, At, B1); PG8_BAR;
.LBB0_501:
	ds_read_b128 v[148:151], v228
	ds_read_b128 v[152:155], v228 offset:1024
	ds_read_b128 v[156:159], v228 offset:2048
	ds_read_b128 v[176:179], v228 offset:3072
	s_add_i32 m0, s52, 0xc000
	ds_read_b128 v[180:183], v146
	ds_read_b128 v[184:187], v146 offset:1024
	ds_read_b128 v[188:191], v146 offset:2048
	ds_read_b128 v[192:195], v146 offset:3072
	ds_read_b128 v[196:199], v146 offset:4096
	ds_read_b128 v[200:203], v146 offset:5120
	ds_read_b128 v[204:207], v146 offset:6144
	ds_read_b128 v[208:211], v146 offset:7168
	global_load_lds_dwordx4 v132, s[54:55]
	s_add_i32 m0, s52, 0xe000
	s_nop 0
	global_load_lds_dwordx4 v138, s[54:55]
	s_add_u32 s4, s54, 0x4000
	s_addc_u32 s5, s55, 0
	s_cmp_eq_u32 s49, 28
	s_cselect_b32 s4, s50, s4
	s_cselect_b32 s5, s51, s5
	s_cselect_b32 s56, s40, s29
	s_cselect_b32 s57, s41, s47
	s_add_u32 s58, s4, 0x8000
	s_addc_u32 s59, s5, 0
	s_add_i32 s69, 0, 0x10000
	s_waitcnt lgkmcnt(8)
	s_barrier
	s_waitcnt lgkmcnt(0)
	s_setprio 1
	v_mfma_f32_16x16x32_bf16 v[128:131], v[148:151], v[180:183], v[128:131]
	v_mfma_f32_16x16x32_bf16 v[124:127], v[156:159], v[180:183], v[124:127]
	v_mfma_f32_16x16x32_bf16 v[120:123], v[148:151], v[188:191], v[120:123]
	v_mfma_f32_16x16x32_bf16 v[116:119], v[156:159], v[188:191], v[116:119]
	v_mfma_f32_16x16x32_bf16 v[104:107], v[148:151], v[196:199], v[104:107]
	v_mfma_f32_16x16x32_bf16 v[100:103], v[156:159], v[196:199], v[100:103]
	v_mfma_f32_16x16x32_bf16 v[88:91], v[148:151], v[204:207], v[88:91]
	v_mfma_f32_16x16x32_bf16 v[84:87], v[156:159], v[204:207], v[84:87]
	v_mfma_f32_16x16x32_bf16 v[128:131], v[152:155], v[184:187], v[128:131]
	v_mfma_f32_16x16x32_bf16 v[124:127], v[176:179], v[184:187], v[124:127]
	v_mfma_f32_16x16x32_bf16 v[120:123], v[152:155], v[192:195], v[120:123]
	v_mfma_f32_16x16x32_bf16 v[116:119], v[176:179], v[192:195], v[116:119]
	v_mfma_f32_16x16x32_bf16 v[104:107], v[152:155], v[200:203], v[104:107]
	v_mfma_f32_16x16x32_bf16 v[100:103], v[176:179], v[200:203], v[100:103]
	s_setprio 2
	s_barrier
	v_mfma_f32_16x16x32_bf16 v[88:91], v[152:155], v[208:211], v[88:91]
	v_mfma_f32_16x16x32_bf16 v[84:87], v[176:179], v[208:211], v[84:87]
	s_setprio 0
	s_add_i32 s72, 0, 0x14000
	s_add_i32 s69, s69, s39
	ds_read_b128 v[212:215], v228 offset:16384
	ds_read_b128 v[216:219], v228 offset:17408
	ds_read_b128 v[220:223], v228 offset:18432
	ds_read_b128 v[224:227], v228 offset:19456
	s_mov_b32 m0, s69
	s_nop 0
	global_load_lds_dwordx4 v132, s[56:57]
	s_add_i32 m0, s69, 0x2000
	s_nop 0
	global_load_lds_dwordx4 v138, s[56:57]
	s_barrier
	s_waitcnt lgkmcnt(0)
	s_setprio 1
	v_mfma_f32_16x16x32_bf16 v[112:115], v[212:215], v[180:183], v[112:115]
	v_mfma_f32_16x16x32_bf16 v[108:111], v[220:223], v[180:183], v[108:111]
	v_mfma_f32_16x16x32_bf16 v[96:99], v[212:215], v[188:191], v[96:99]
	v_mfma_f32_16x16x32_bf16 v[92:95], v[220:223], v[188:191], v[92:95]
	v_mfma_f32_16x16x32_bf16 v[80:83], v[212:215], v[196:199], v[80:83]
	v_mfma_f32_16x16x32_bf16 v[76:79], v[220:223], v[196:199], v[76:79]
	v_mfma_f32_16x16x32_bf16 v[72:75], v[212:215], v[204:207], v[72:75]
	v_mfma_f32_16x16x32_bf16 v[68:71], v[220:223], v[204:207], v[68:71]
	v_mfma_f32_16x16x32_bf16 v[112:115], v[216:219], v[184:187], v[112:115]
	v_mfma_f32_16x16x32_bf16 v[108:111], v[224:227], v[184:187], v[108:111]
	v_mfma_f32_16x16x32_bf16 v[96:99], v[216:219], v[192:195], v[96:99]
	v_mfma_f32_16x16x32_bf16 v[92:95], v[224:227], v[192:195], v[92:95]
	v_mfma_f32_16x16x32_bf16 v[80:83], v[216:219], v[200:203], v[80:83]
	v_mfma_f32_16x16x32_bf16 v[76:79], v[224:227], v[200:203], v[76:79]
	s_setprio 2
	s_mov_b32 m0, s52
	s_barrier
	v_mfma_f32_16x16x32_bf16 v[72:75], v[216:219], v[208:211], v[72:75]
	v_mfma_f32_16x16x32_bf16 v[68:71], v[224:227], v[208:211], v[68:71]
	s_setprio 0
	ds_read_b128 v[180:183], v146 offset:16384
	ds_read_b128 v[184:187], v146 offset:17408
	ds_read_b128 v[188:191], v146 offset:18432
	ds_read_b128 v[192:195], v146 offset:19456
	ds_read_b128 v[196:199], v146 offset:20480
	ds_read_b128 v[200:203], v146 offset:21504
	ds_read_b128 v[204:207], v146 offset:22528
	ds_read_b128 v[208:211], v146 offset:23552
	global_load_lds_dwordx4 v132, s[4:5]
	s_mov_b32 m0, s53
	s_nop 0
	global_load_lds_dwordx4 v138, s[4:5]
	s_barrier
	s_waitcnt lgkmcnt(0)
	s_setprio 1
	v_mfma_f32_16x16x32_bf16 v[64:67], v[148:151], v[180:183], v[64:67]
	v_mfma_f32_16x16x32_bf16 v[60:63], v[156:159], v[180:183], v[60:63]
	v_mfma_f32_16x16x32_bf16 v[56:59], v[148:151], v[188:191], v[56:59]
	v_mfma_f32_16x16x32_bf16 v[52:55], v[156:159], v[188:191], v[52:55]
	v_mfma_f32_16x16x32_bf16 v[40:43], v[148:151], v[196:199], v[40:43]
	v_mfma_f32_16x16x32_bf16 v[36:39], v[156:159], v[196:199], v[36:39]
	v_mfma_f32_16x16x32_bf16 v[24:27], v[148:151], v[204:207], v[24:27]
	v_mfma_f32_16x16x32_bf16 v[20:23], v[156:159], v[204:207], v[20:23]
	v_mfma_f32_16x16x32_bf16 v[64:67], v[152:155], v[184:187], v[64:67]
	v_mfma_f32_16x16x32_bf16 v[60:63], v[176:179], v[184:187], v[60:63]
	v_mfma_f32_16x16x32_bf16 v[56:59], v[152:155], v[192:195], v[56:59]
	v_mfma_f32_16x16x32_bf16 v[52:55], v[176:179], v[192:195], v[52:55]
	v_mfma_f32_16x16x32_bf16 v[40:43], v[152:155], v[200:203], v[40:43]
	v_mfma_f32_16x16x32_bf16 v[36:39], v[176:179], v[200:203], v[36:39]
	s_setprio 2
	s_barrier
	v_mfma_f32_16x16x32_bf16 v[24:27], v[152:155], v[208:211], v[24:27]
	v_mfma_f32_16x16x32_bf16 v[20:23], v[176:179], v[208:211], v[20:23]
	s_setprio 0
	s_add_u32 s70, s56, 0x4000
	s_addc_u32 s71, s57, 0
	s_add_i32 s69, s72, s39
	s_mov_b32 m0, s69
	s_nop 0
	global_load_lds_dwordx4 v132, s[70:71]
	s_add_i32 m0, s69, 0x2000
	s_nop 0
	global_load_lds_dwordx4 v138, s[70:71]
	s_waitcnt vmcnt(6)
	s_barrier
; #define PG8_STAGE(bufoff, gbase, voff) do { _Pragma("unroll") for (int _i = 0; _i < 2; ++_i) \
;         __builtin_amdgcn_global_load_lds((const unsigned*)((const char*)(gbase) + (voff)[_i]), (LAS unsigned*)(lds + (bufoff) + ldsw + _i * 8192), 16, 0, 0); } while (0)
; #define PG8_LDA(dst, b, h) do { _Pragma("unroll") for (int m = 0; m < 4; ++m) _Pragma("unroll") for (int k = 0; k < 2; ++k) dst[m][k] = *(const LAS bf16x8*)(lds + PG8_SA(b, h) + aoff + m * 2048 + k * 1024); } while (0)
; #define PG8_LDB(dst, b, h) do { _Pragma("unroll") for (int n = 0; n < 2; ++n) _Pragma("unroll") for (int k = 0; k < 2; ++k) dst[n][k] = *(const LAS bf16x8*)(lds + PG8_SB(b, h) + boff + n * 2048 + k * 1024); } while (0)
; #define PG8_MMA(ai, bj, At, Bt) do { __builtin_amdgcn_s_setprio(1); _Pragma("unroll") for (int m = 0; m < 4; ++m) _Pragma("unroll") for (int n = 0; n < 2; ++n) _Pragma("unroll") for (int k = 0; k < 2; ++k) \
;         acc[ai][bj][m][n] = __builtin_amdgcn_mfma_f32_16x16x32_bf16(Bt[n][k], At[m][k], acc[ai][bj][m][n], 0, 0, 0); __builtin_amdgcn_s_setprio(0); } while (0)
; #define PG8_WAIT_V(n) asm volatile("s_waitcnt vmcnt(" #n ")" ::: "memory")
; #define PG8_WAIT_L(n) asm volatile("s_waitcnt lgkmcnt(" #n ")" ::: "memory")
; #define PG8_BAR __builtin_amdgcn_s_barrier()
; #define PG8_SCHED __builtin_amdgcn_sched_barrier(0)
; template <class Epi, class Sched, int LD>
; __device__ __forceinline__ void gemm_phase(LAS unsigned char* lds, const Gemm g, const Sched& S, const Epi& E) {
;     ...
;             PG8_WAIT_V(6); PG8_BAR; PG8_MMA(1, 1, At, B1); PG8_BAR;
;             PG8_LDB(B0, 1, 0); PG8_SCHED; PG8_LDA(At, 1, 0); PG8_STAGE(PG8_SA(0, 1), a2 + hstep, voffA);
;             PG8_WAIT_L(8); PG8_BAR; PG8_WAIT_L(0); PG8_MMA(0, 0, At, B0); PG8_BAR; PG8_SCHED;
;             PG8_LDB(B1, 1, 1); PG8_STAGE(PG8_SB(1, 0), b3, voffB);
;             PG8_BAR; PG8_WAIT_L(0); PG8_MMA(0, 1, At, B1); PG8_BAR;
;             PG8_LDA(At, 1, 1); PG8_STAGE(PG8_SA(1, 0), a3, voffA);
	s_setprio 1
	v_mfma_f32_16x16x32_bf16 v[48:51], v[212:215], v[180:183], v[48:51]
	v_mfma_f32_16x16x32_bf16 v[44:47], v[220:223], v[180:183], v[44:47]
	v_mfma_f32_16x16x32_bf16 v[32:35], v[212:215], v[188:191], v[32:35]
	v_mfma_f32_16x16x32_bf16 v[28:31], v[220:223], v[188:191], v[28:31]
	v_mfma_f32_16x16x32_bf16 v[16:19], v[212:215], v[196:199], v[16:19]
	v_mfma_f32_16x16x32_bf16 v[12:15], v[220:223], v[196:199], v[12:15]
	v_mfma_f32_16x16x32_bf16 v[8:11], v[212:215], v[204:207], v[8:11]
	v_mfma_f32_16x16x32_bf16 v[4:7], v[220:223], v[204:207], v[4:7]
	v_mfma_f32_16x16x32_bf16 v[48:51], v[216:219], v[184:187], v[48:51]
	v_mfma_f32_16x16x32_bf16 v[44:47], v[224:227], v[184:187], v[44:47]
	v_mfma_f32_16x16x32_bf16 v[32:35], v[216:219], v[192:195], v[32:35]
	v_mfma_f32_16x16x32_bf16 v[28:31], v[224:227], v[192:195], v[28:31]
	v_mfma_f32_16x16x32_bf16 v[16:19], v[216:219], v[200:203], v[16:19]
	v_mfma_f32_16x16x32_bf16 v[12:15], v[224:227], v[200:203], v[12:15]
	s_setprio 2
	s_add_i32 s69, 0, 0x18000
	s_barrier
	v_mfma_f32_16x16x32_bf16 v[8:11], v[216:219], v[208:211], v[8:11]
	v_mfma_f32_16x16x32_bf16 v[4:7], v[224:227], v[208:211], v[4:7]
	s_setprio 0
	ds_read_b128 v[148:151], v228 offset:32768
	ds_read_b128 v[152:155], v228 offset:33792
	ds_read_b128 v[156:159], v228 offset:34816
	ds_read_b128 v[176:179], v228 offset:35840
	s_add_u32 s4, s4, 0x4000
	s_addc_u32 s5, s5, 0
	s_mov_b32 m0, s60
	ds_read_b128 v[180:183], v146 offset:32768
	ds_read_b128 v[184:187], v146 offset:33792
	ds_read_b128 v[188:191], v146 offset:34816
	ds_read_b128 v[192:195], v146 offset:35840
	ds_read_b128 v[196:199], v146 offset:36864
	ds_read_b128 v[200:203], v146 offset:37888
	ds_read_b128 v[204:207], v146 offset:38912
	ds_read_b128 v[208:211], v146 offset:39936
	global_load_lds_dwordx4 v132, s[4:5]
	s_mov_b32 m0, s61
	s_nop 0
	global_load_lds_dwordx4 v138, s[4:5]
	s_waitcnt lgkmcnt(8)
	s_barrier
	s_waitcnt lgkmcnt(0)
	s_setprio 1
	v_mfma_f32_16x16x32_bf16 v[128:131], v[148:151], v[180:183], v[128:131]
	v_mfma_f32_16x16x32_bf16 v[124:127], v[156:159], v[180:183], v[124:127]
	v_mfma_f32_16x16x32_bf16 v[120:123], v[148:151], v[188:191], v[120:123]
	v_mfma_f32_16x16x32_bf16 v[116:119], v[156:159], v[188:191], v[116:119]
	v_mfma_f32_16x16x32_bf16 v[104:107], v[148:151], v[196:199], v[104:107]
	v_mfma_f32_16x16x32_bf16 v[100:103], v[156:159], v[196:199], v[100:103]
	v_mfma_f32_16x16x32_bf16 v[88:91], v[148:151], v[204:207], v[88:91]
	v_mfma_f32_16x16x32_bf16 v[84:87], v[156:159], v[204:207], v[84:87]
	v_mfma_f32_16x16x32_bf16 v[128:131], v[152:155], v[184:187], v[128:131]
	v_mfma_f32_16x16x32_bf16 v[124:127], v[176:179], v[184:187], v[124:127]
	v_mfma_f32_16x16x32_bf16 v[120:123], v[152:155], v[192:195], v[120:123]
	v_mfma_f32_16x16x32_bf16 v[116:119], v[176:179], v[192:195], v[116:119]
	v_mfma_f32_16x16x32_bf16 v[104:107], v[152:155], v[200:203], v[104:107]
	v_mfma_f32_16x16x32_bf16 v[100:103], v[176:179], v[200:203], v[100:103]
	s_setprio 2
	s_barrier
	v_mfma_f32_16x16x32_bf16 v[88:91], v[152:155], v[208:211], v[88:91]
	v_mfma_f32_16x16x32_bf16 v[84:87], v[176:179], v[208:211], v[84:87]
	s_setprio 0
	s_add_i32 s70, 0, 0x1c000
	s_add_u32 s4, s56, 0x8000
	s_addc_u32 s5, s57, 0
	s_add_i32 s69, s69, s39
	ds_read_b128 v[212:215], v228 offset:49152
	ds_read_b128 v[216:219], v228 offset:50176
	ds_read_b128 v[220:223], v228 offset:51200
	ds_read_b128 v[224:227], v228 offset:52224
	s_mov_b32 m0, s69
	s_nop 0
	global_load_lds_dwordx4 v132, s[4:5]
	s_add_i32 m0, s69, 0x2000
	s_nop 0
	global_load_lds_dwordx4 v138, s[4:5]
	s_barrier
	s_waitcnt lgkmcnt(0)
	s_setprio 1
	v_mfma_f32_16x16x32_bf16 v[112:115], v[212:215], v[180:183], v[112:115]
	v_mfma_f32_16x16x32_bf16 v[108:111], v[220:223], v[180:183], v[108:111]
	v_mfma_f32_16x16x32_bf16 v[96:99], v[212:215], v[188:191], v[96:99]
	v_mfma_f32_16x16x32_bf16 v[92:95], v[220:223], v[188:191], v[92:95]
	v_mfma_f32_16x16x32_bf16 v[80:83], v[212:215], v[196:199], v[80:83]
	v_mfma_f32_16x16x32_bf16 v[76:79], v[220:223], v[196:199], v[76:79]
	v_mfma_f32_16x16x32_bf16 v[72:75], v[212:215], v[204:207], v[72:75]
	v_mfma_f32_16x16x32_bf16 v[68:71], v[220:223], v[204:207], v[68:71]
	v_mfma_f32_16x16x32_bf16 v[112:115], v[216:219], v[184:187], v[112:115]
	v_mfma_f32_16x16x32_bf16 v[108:111], v[224:227], v[184:187], v[108:111]
	v_mfma_f32_16x16x32_bf16 v[96:99], v[216:219], v[192:195], v[96:99]
	v_mfma_f32_16x16x32_bf16 v[92:95], v[224:227], v[192:195], v[92:95]
	v_mfma_f32_16x16x32_bf16 v[80:83], v[216:219], v[200:203], v[80:83]
	v_mfma_f32_16x16x32_bf16 v[76:79], v[224:227], v[200:203], v[76:79]
	s_setprio 2
	s_mov_b32 m0, s64
	s_barrier
	v_mfma_f32_16x16x32_bf16 v[72:75], v[216:219], v[208:211], v[72:75]
	v_mfma_f32_16x16x32_bf16 v[68:71], v[224:227], v[208:211], v[68:71]
	s_setprio 0
	ds_read_b128 v[180:183], v146 offset:49152
	ds_read_b128 v[184:187], v146 offset:50176
	ds_read_b128 v[188:191], v146 offset:51200
	ds_read_b128 v[192:195], v146 offset:52224
	ds_read_b128 v[196:199], v146 offset:53248
	ds_read_b128 v[200:203], v146 offset:54272
	ds_read_b128 v[204:207], v146 offset:55296
	ds_read_b128 v[208:211], v146 offset:56320
	global_load_lds_dwordx4 v132, s[58:59]
	s_mov_b32 m0, s65
	s_nop 0
	global_load_lds_dwordx4 v138, s[58:59]
	s_barrier
; #define PG8_STAGE(bufoff, gbase, voff) do { _Pragma("unroll") for (int _i = 0; _i < 2; ++_i) \
;         __builtin_amdgcn_global_load_lds((const unsigned*)((const char*)(gbase) + (voff)[_i]), (LAS unsigned*)(lds + (bufoff) + ldsw + _i * 8192), 16, 0, 0); } while (0)
; #define PG8_MMA(ai, bj, At, Bt) do { __builtin_amdgcn_s_setprio(1); _Pragma("unroll") for (int m = 0; m < 4; ++m) _Pragma("unroll") for (int n = 0; n < 2; ++n) _Pragma("unroll") for (int k = 0; k < 2; ++k) \
;         acc[ai][bj][m][n] = __builtin_amdgcn_mfma_f32_16x16x32_bf16(Bt[n][k], At[m][k], acc[ai][bj][m][n], 0, 0, 0); __builtin_amdgcn_s_setprio(0); } while (0)
; #define PG8_WAIT_V(n) asm volatile("s_waitcnt vmcnt(" #n ")" ::: "memory")
; #define PG8_WAIT_L(n) asm volatile("s_waitcnt lgkmcnt(" #n ")" ::: "memory")
; #define PG8_BAR __builtin_amdgcn_s_barrier()
; #define PG8_SCHED __builtin_amdgcn_sched_barrier(0)
;     __device__ __forceinline__ void operator()(const f32x4 (&acc)[2][2][4][2], const Unit& u, int wr, int wc, int fr, int fq) const {
;     ...
;         } else if (wc == 0) {
; #pragma unroll
;             for (int ai = 0; ai < 2; ++ai)
; #pragma unroll
;                 for (int m = 0; m < 4; ++m) {
;                     float* rowp = DT + (size_t)(row0 + ai * HALF + m * 16) * 32 + 8 * fq;
;                     *(f32x4*)rowp = acc[ai][0][m][0]; *(f32x4*)(rowp + 4) = acc[ai][0][m][1];
;                 }
; template <class Epi, class Sched, int LD>
; __device__ __forceinline__ void gemm_phase(LAS unsigned char* lds, const Gemm g, const Sched& S, const Epi& E) {
;     ...
;             PG8_BAR; PG8_WAIT_L(0); PG8_MMA(1, 0, At, B0); PG8_BAR; PG8_SCHED;
;             PG8_STAGE(PG8_SB(1, 1), b3 + hstep, voffB);
;             PG8_WAIT_V(6); PG8_BAR; PG8_MMA(1, 1, At, B1); PG8_BAR;
	s_waitcnt lgkmcnt(0)
	s_setprio 1
	v_mfma_f32_16x16x32_bf16 v[64:67], v[148:151], v[180:183], v[64:67]
	v_mfma_f32_16x16x32_bf16 v[60:63], v[156:159], v[180:183], v[60:63]
	v_mfma_f32_16x16x32_bf16 v[56:59], v[148:151], v[188:191], v[56:59]
	v_mfma_f32_16x16x32_bf16 v[52:55], v[156:159], v[188:191], v[52:55]
	v_mfma_f32_16x16x32_bf16 v[40:43], v[148:151], v[196:199], v[40:43]
	v_mfma_f32_16x16x32_bf16 v[36:39], v[156:159], v[196:199], v[36:39]
	v_mfma_f32_16x16x32_bf16 v[24:27], v[148:151], v[204:207], v[24:27]
	v_mfma_f32_16x16x32_bf16 v[20:23], v[156:159], v[204:207], v[20:23]
	v_mfma_f32_16x16x32_bf16 v[64:67], v[152:155], v[184:187], v[64:67]
	v_mfma_f32_16x16x32_bf16 v[60:63], v[176:179], v[184:187], v[60:63]
	v_mfma_f32_16x16x32_bf16 v[56:59], v[152:155], v[192:195], v[56:59]
	v_mfma_f32_16x16x32_bf16 v[52:55], v[176:179], v[192:195], v[52:55]
	v_mfma_f32_16x16x32_bf16 v[40:43], v[152:155], v[200:203], v[40:43]
	v_mfma_f32_16x16x32_bf16 v[36:39], v[176:179], v[200:203], v[36:39]
	s_setprio 2
	s_barrier
	v_mfma_f32_16x16x32_bf16 v[24:27], v[152:155], v[208:211], v[24:27]
	v_mfma_f32_16x16x32_bf16 v[20:23], v[176:179], v[208:211], v[20:23]
	s_setprio 0
	s_add_u32 s4, s56, 0xc000
	s_addc_u32 s5, s57, 0
	s_add_i32 s56, s70, s39
	s_mov_b32 m0, s56
	s_nop 0
	global_load_lds_dwordx4 v132, s[4:5]
	s_add_i32 m0, s56, 0x2000
	s_nop 0
	global_load_lds_dwordx4 v138, s[4:5]
	s_waitcnt vmcnt(6)
	s_barrier
	s_setprio 1
	v_mfma_f32_16x16x32_bf16 v[48:51], v[212:215], v[180:183], v[48:51]
	v_mfma_f32_16x16x32_bf16 v[44:47], v[220:223], v[180:183], v[44:47]
	v_mfma_f32_16x16x32_bf16 v[32:35], v[212:215], v[188:191], v[32:35]
	v_mfma_f32_16x16x32_bf16 v[28:31], v[220:223], v[188:191], v[28:31]
	v_mfma_f32_16x16x32_bf16 v[16:19], v[212:215], v[196:199], v[16:19]
	v_mfma_f32_16x16x32_bf16 v[12:15], v[220:223], v[196:199], v[12:15]
	v_mfma_f32_16x16x32_bf16 v[8:11], v[212:215], v[204:207], v[8:11]
	v_mfma_f32_16x16x32_bf16 v[4:7], v[220:223], v[204:207], v[4:7]
	v_mfma_f32_16x16x32_bf16 v[48:51], v[216:219], v[184:187], v[48:51]
	v_mfma_f32_16x16x32_bf16 v[44:47], v[224:227], v[184:187], v[44:47]
	v_mfma_f32_16x16x32_bf16 v[32:35], v[216:219], v[192:195], v[32:35]
	v_mfma_f32_16x16x32_bf16 v[28:31], v[224:227], v[192:195], v[28:31]
	v_mfma_f32_16x16x32_bf16 v[16:19], v[216:219], v[200:203], v[16:19]
	v_mfma_f32_16x16x32_bf16 v[12:15], v[224:227], v[200:203], v[12:15]
	s_setprio 2
	s_add_i32 s49, s49, 2
	s_add_u32 s54, s54, 0x10000
	s_addc_u32 s55, s55, 0
	s_add_u32 s29, s29, 0x10000
	s_addc_u32 s47, s47, 0
	s_cmp_gt_u32 s49, 29
	s_barrier
	v_mfma_f32_16x16x32_bf16 v[8:11], v[216:219], v[208:211], v[8:11]
	v_mfma_f32_16x16x32_bf16 v[4:7], v[224:227], v[208:211], v[4:7]
	s_setprio 0
	s_cbranch_scc0 .LBB0_501
	v_lshl_add_u32 v142, s68, 8, v137
	s_cmp_gt_i32 s67, 35
	s_mov_b64 s[4:5], -1
	s_cbranch_scc0 .LBB0_506
	s_andn2_b64 vcc, exec, s[42:43]
	s_cbranch_vccnz .LBB0_505
	v_or_b32_e32 v150, 16, v142
	v_ashrrev_i32_e32 v143, 31, v142
	v_ashrrev_i32_e32 v151, 31, v150
	v_lshlrev_b64 v[148:149], 7, v[142:143]
	v_lshlrev_b64 v[150:151], 7, v[150:151]
	v_lshl_add_u64 v[148:149], v[140:141], 0, v[148:149]
	v_lshl_add_u64 v[150:151], v[140:141], 0, v[150:151]
	global_store_dwordx4 v[148:149], v[128:131], off
	global_store_dwordx4 v[148:149], v[124:127], off offset:16
	global_store_dwordx4 v[150:151], v[120:123], off
	global_store_dwordx4 v[150:151], v[116:119], off offset:16
	v_or_b32_e32 v150, 32, v142
	v_ashrrev_i32_e32 v151, 31, v150
	v_lshlrev_b64 v[150:151], 7, v[150:151]
	v_lshl_add_u64 v[150:151], v[140:141], 0, v[150:151]
	global_store_dwordx4 v[150:151], v[104:107], off
	global_store_dwordx4 v[150:151], v[100:103], off offset:16
	v_or_b32_e32 v150, 48, v142
	v_ashrrev_i32_e32 v151, 31, v150
	v_lshlrev_b64 v[150:151], 7, v[150:151]
	v_lshl_add_u64 v[150:151], v[140:141], 0, v[150:151]
	s_mov_b64 s[4:5], 0x4000
	global_store_dwordx4 v[150:151], v[88:91], off
	global_store_dwordx4 v[150:151], v[84:87], off offset:16
	v_lshl_add_u64 v[150:151], v[148:149], 0, s[4:5]
	s_movk_i32 s4, 0x4000
	v_add_co_u32_e32 v152, vcc, s4, v148
	s_mov_b64 s[4:5], 0x4800
	s_nop 0
	v_addc_co_u32_e32 v153, vcc, 0, v149, vcc
	global_store_dwordx4 v[152:153], v[64:67], off
	global_store_dwordx4 v[150:151], v[60:63], off offset:16
	v_lshl_add_u64 v[150:151], v[148:149], 0, s[4:5]
	global_store_dwordx4 v[152:153], v[56:59], off offset:2048
	global_store_dwordx4 v[150:151], v[52:55], off offset:16
	s_mov_b64 s[4:5], 0x5000
	v_add_co_u32_e32 v152, vcc, 0x5000, v148
	v_lshl_add_u64 v[150:151], v[148:149], 0, s[4:5]
	s_nop 0
	v_addc_co_u32_e32 v153, vcc, 0, v149, vcc
	s_mov_b64 s[4:5], 0x5800
	global_store_dwordx4 v[152:153], v[40:43], off
	global_store_dwordx4 v[150:151], v[36:39], off offset:16
	v_lshl_add_u64 v[148:149], v[148:149], 0, s[4:5]
	global_store_dwordx4 v[152:153], v[24:27], off offset:2048
	global_store_dwordx4 v[148:149], v[20:23], off offset:16

; #define PG8_STAGE(bufoff, gbase, voff) do { _Pragma("unroll") for (int _i = 0; _i < 2; ++_i) \
;         __builtin_amdgcn_global_load_lds((const unsigned*)((const char*)(gbase) + (voff)[_i]), (LAS unsigned*)(lds + (bufoff) + ldsw + _i * 8192), 16, 0, 0); } while (0)
; #define PG8_LDA(dst, b, h) do { _Pragma("unroll") for (int m = 0; m < 4; ++m) _Pragma("unroll") for (int k = 0; k < 2; ++k) dst[m][k] = *(const LAS bf16x8*)(lds + PG8_SA(b, h) + aoff + m * 2048 + k * 1024); } while (0)
; #define PG8_LDB(dst, b, h) do { _Pragma("unroll") for (int n = 0; n < 2; ++n) _Pragma("unroll") for (int k = 0; k < 2; ++k) dst[n][k] = *(const LAS bf16x8*)(lds + PG8_SB(b, h) + boff + n * 2048 + k * 1024); } while (0)
; #define PG8_MMA(ai, bj, At, Bt) do { __builtin_amdgcn_s_setprio(1); _Pragma("unroll") for (int m = 0; m < 4; ++m) _Pragma("unroll") for (int n = 0; n < 2; ++n) _Pragma("unroll") for (int k = 0; k < 2; ++k) \
;         acc[ai][bj][m][n] = __builtin_amdgcn_mfma_f32_16x16x32_bf16(Bt[n][k], At[m][k], acc[ai][bj][m][n], 0, 0, 0); __builtin_amdgcn_s_setprio(0); } while (0)
; #define PG8_WAIT_V(n) asm volatile("s_waitcnt vmcnt(" #n ")" ::: "memory")
; #define PG8_WAIT_L(n) asm volatile("s_waitcnt lgkmcnt(" #n ")" ::: "memory")
; #define PG8_BAR __builtin_amdgcn_s_barrier()
; template <class Epi, class Sched, int LD>
; __device__ __forceinline__ void gemm_phase(LAS unsigned char* lds, const Gemm g, const Sched& S, const Epi& E) {
;     ...
;             const bool last = (t == nt - 2);
;             const char* a1 = cA + (size_t)(t + 1) * kstep;
;             const char* a2 = last ? nA : cA + (size_t)(t + 2) * kstep; const char* b2 = last ? nB : cB + (size_t)(t + 2) * kstep;
;             const char* a3 = a2 + kstep; const char* b3 = b2 + kstep;
;             PG8_LDB(B0, 0, 0); PG8_SCHED; PG8_LDA(At, 0, 0); PG8_STAGE(PG8_SA(1, 1), a1 + hstep, voffA);
;             PG8_WAIT_L(8); PG8_BAR; PG8_WAIT_L(0); PG8_MMA(0, 0, At, B0); PG8_BAR; PG8_SCHED;
;             PG8_LDB(B1, 0, 1); PG8_STAGE(PG8_SB(0, 0), b2, voffB);
;             PG8_BAR; PG8_WAIT_L(0); PG8_MMA(0, 1, At, B1); PG8_BAR;
;             PG8_LDA(At, 0, 1); PG8_STAGE(PG8_SA(0, 0), a2, voffA);
;             PG8_BAR; PG8_WAIT_L(0); PG8_MMA(1, 0, At, B0); PG8_BAR; PG8_SCHED;
;             PG8_STAGE(PG8_SB(0, 1), b2 + hstep, voffB);
;             PG8_WAIT_V(6); PG8_BAR; PG8_MMA(1, 1, At, B1); PG8_BAR;
.LBB0_899:
	ds_read_b128 v[146:149], v228
	ds_read_b128 v[150:153], v228 offset:1024
	ds_read_b128 v[154:157], v228 offset:2048
	ds_read_b128 v[176:179], v228 offset:3072
	s_add_i32 m0, s29, 0xc000
	ds_read_b128 v[180:183], v144
	ds_read_b128 v[184:187], v144 offset:1024
	ds_read_b128 v[188:191], v144 offset:2048
	ds_read_b128 v[192:195], v144 offset:3072
	ds_read_b128 v[196:199], v144 offset:4096
	ds_read_b128 v[200:203], v144 offset:5120
	ds_read_b128 v[204:207], v144 offset:6144
	ds_read_b128 v[208:211], v144 offset:7168
	global_load_lds_dwordx4 v138, s[50:51]
	s_add_i32 m0, s29, 0xe000
	s_nop 0
	global_load_lds_dwordx4 v140, s[50:51]
	s_add_u32 s4, s50, 0x4000
	s_addc_u32 s5, s51, 0
	s_cmp_eq_u32 s70, 28
	s_cselect_b32 s4, s48, s4
	s_cselect_b32 s5, s49, s5
	s_cselect_b32 s54, s40, s45
	s_cselect_b32 s55, s41, s47
	s_add_u32 s56, s4, 0x8000
	s_addc_u32 s57, s5, 0
	s_add_i32 s71, 0, 0x10000
	s_waitcnt lgkmcnt(8)
	s_barrier
	s_waitcnt lgkmcnt(0)
	s_setprio 1
	v_mfma_f32_16x16x32_bf16 v[128:131], v[146:149], v[180:183], v[128:131]
	v_mfma_f32_16x16x32_bf16 v[120:123], v[154:157], v[180:183], v[120:123]
	v_mfma_f32_16x16x32_bf16 v[112:115], v[146:149], v[188:191], v[112:115]
	v_mfma_f32_16x16x32_bf16 v[104:107], v[154:157], v[188:191], v[104:107]
	v_mfma_f32_16x16x32_bf16 v[96:99], v[146:149], v[196:199], v[96:99]
	v_mfma_f32_16x16x32_bf16 v[88:91], v[154:157], v[196:199], v[88:91]
	v_mfma_f32_16x16x32_bf16 v[80:83], v[146:149], v[204:207], v[80:83]
	v_mfma_f32_16x16x32_bf16 v[72:75], v[154:157], v[204:207], v[72:75]
	v_mfma_f32_16x16x32_bf16 v[128:131], v[150:153], v[184:187], v[128:131]
	v_mfma_f32_16x16x32_bf16 v[120:123], v[176:179], v[184:187], v[120:123]
	v_mfma_f32_16x16x32_bf16 v[112:115], v[150:153], v[192:195], v[112:115]
	v_mfma_f32_16x16x32_bf16 v[104:107], v[176:179], v[192:195], v[104:107]
	v_mfma_f32_16x16x32_bf16 v[96:99], v[150:153], v[200:203], v[96:99]
	v_mfma_f32_16x16x32_bf16 v[88:91], v[176:179], v[200:203], v[88:91]
	s_setprio 2
	s_barrier
	v_mfma_f32_16x16x32_bf16 v[80:83], v[150:153], v[208:211], v[80:83]
	v_mfma_f32_16x16x32_bf16 v[72:75], v[176:179], v[208:211], v[72:75]
	s_setprio 0
	s_add_i32 s74, 0, 0x14000
	s_add_i32 s71, s71, s28
	s_mov_b32 m0, s71
	ds_read_b128 v[212:215], v228 offset:16384
	ds_read_b128 v[216:219], v228 offset:17408
	ds_read_b128 v[220:223], v228 offset:18432
	ds_read_b128 v[224:227], v228 offset:19456
	global_load_lds_dwordx4 v138, s[54:55]
	s_add_i32 m0, s71, 0x2000
	s_nop 0
	global_load_lds_dwordx4 v140, s[54:55]
	s_barrier
	s_waitcnt lgkmcnt(0)
	s_setprio 1
	v_mfma_f32_16x16x32_bf16 v[124:127], v[212:215], v[180:183], v[124:127]
	v_mfma_f32_16x16x32_bf16 v[116:119], v[220:223], v[180:183], v[116:119]
	v_mfma_f32_16x16x32_bf16 v[108:111], v[212:215], v[188:191], v[108:111]
	v_mfma_f32_16x16x32_bf16 v[100:103], v[220:223], v[188:191], v[100:103]
	v_mfma_f32_16x16x32_bf16 v[92:95], v[212:215], v[196:199], v[92:95]
	v_mfma_f32_16x16x32_bf16 v[84:87], v[220:223], v[196:199], v[84:87]
	v_mfma_f32_16x16x32_bf16 v[76:79], v[212:215], v[204:207], v[76:79]
	v_mfma_f32_16x16x32_bf16 v[68:71], v[220:223], v[204:207], v[68:71]
	v_mfma_f32_16x16x32_bf16 v[124:127], v[216:219], v[184:187], v[124:127]
	v_mfma_f32_16x16x32_bf16 v[116:119], v[224:227], v[184:187], v[116:119]
	v_mfma_f32_16x16x32_bf16 v[108:111], v[216:219], v[192:195], v[108:111]
	v_mfma_f32_16x16x32_bf16 v[100:103], v[224:227], v[192:195], v[100:103]
	v_mfma_f32_16x16x32_bf16 v[92:95], v[216:219], v[200:203], v[92:95]
	v_mfma_f32_16x16x32_bf16 v[84:87], v[224:227], v[200:203], v[84:87]
	s_setprio 2
	s_mov_b32 m0, s29
	s_barrier
	v_mfma_f32_16x16x32_bf16 v[76:79], v[216:219], v[208:211], v[76:79]
	v_mfma_f32_16x16x32_bf16 v[68:71], v[224:227], v[208:211], v[68:71]
	s_setprio 0
	ds_read_b128 v[180:183], v144 offset:16384
	ds_read_b128 v[184:187], v144 offset:17408
	ds_read_b128 v[188:191], v144 offset:18432
	ds_read_b128 v[192:195], v144 offset:19456
	ds_read_b128 v[196:199], v144 offset:20480
	ds_read_b128 v[200:203], v144 offset:21504
	ds_read_b128 v[204:207], v144 offset:22528
	ds_read_b128 v[208:211], v144 offset:23552
	global_load_lds_dwordx4 v138, s[4:5]
	s_mov_b32 m0, s39
	s_nop 0
	global_load_lds_dwordx4 v140, s[4:5]
	s_barrier
	s_waitcnt lgkmcnt(0)
	s_setprio 1
	v_mfma_f32_16x16x32_bf16 v[64:67], v[146:149], v[180:183], v[64:67]
	v_mfma_f32_16x16x32_bf16 v[56:59], v[154:157], v[180:183], v[56:59]
	v_mfma_f32_16x16x32_bf16 v[48:51], v[146:149], v[188:191], v[48:51]
	v_mfma_f32_16x16x32_bf16 v[40:43], v[154:157], v[188:191], v[40:43]
	v_mfma_f32_16x16x32_bf16 v[32:35], v[146:149], v[196:199], v[32:35]
	v_mfma_f32_16x16x32_bf16 v[24:27], v[154:157], v[196:199], v[24:27]
	v_mfma_f32_16x16x32_bf16 v[16:19], v[146:149], v[204:207], v[16:19]
	v_mfma_f32_16x16x32_bf16 v[8:11], v[154:157], v[204:207], v[8:11]
	v_mfma_f32_16x16x32_bf16 v[64:67], v[150:153], v[184:187], v[64:67]
	v_mfma_f32_16x16x32_bf16 v[56:59], v[176:179], v[184:187], v[56:59]
	v_mfma_f32_16x16x32_bf16 v[48:51], v[150:153], v[192:195], v[48:51]
	v_mfma_f32_16x16x32_bf16 v[40:43], v[176:179], v[192:195], v[40:43]
	v_mfma_f32_16x16x32_bf16 v[32:35], v[150:153], v[200:203], v[32:35]
	v_mfma_f32_16x16x32_bf16 v[24:27], v[176:179], v[200:203], v[24:27]
	s_setprio 2
	s_barrier
	v_mfma_f32_16x16x32_bf16 v[16:19], v[150:153], v[208:211], v[16:19]
	v_mfma_f32_16x16x32_bf16 v[8:11], v[176:179], v[208:211], v[8:11]
	s_setprio 0
	s_add_u32 s72, s54, 0x4000
	s_addc_u32 s73, s55, 0
	s_add_i32 s71, s74, s28
	s_mov_b32 m0, s71
	s_nop 0
	global_load_lds_dwordx4 v138, s[72:73]
	s_add_i32 m0, s71, 0x2000
	s_nop 0
	global_load_lds_dwordx4 v140, s[72:73]
	s_waitcnt vmcnt(6)
	s_barrier
; #define PG8_STAGE(bufoff, gbase, voff) do { _Pragma("unroll") for (int _i = 0; _i < 2; ++_i) \
;         __builtin_amdgcn_global_load_lds((const unsigned*)((const char*)(gbase) + (voff)[_i]), (LAS unsigned*)(lds + (bufoff) + ldsw + _i * 8192), 16, 0, 0); } while (0)
; #define PG8_LDA(dst, b, h) do { _Pragma("unroll") for (int m = 0; m < 4; ++m) _Pragma("unroll") for (int k = 0; k < 2; ++k) dst[m][k] = *(const LAS bf16x8*)(lds + PG8_SA(b, h) + aoff + m * 2048 + k * 1024); } while (0)
; #define PG8_LDB(dst, b, h) do { _Pragma("unroll") for (int n = 0; n < 2; ++n) _Pragma("unroll") for (int k = 0; k < 2; ++k) dst[n][k] = *(const LAS bf16x8*)(lds + PG8_SB(b, h) + boff + n * 2048 + k * 1024); } while (0)
; #define PG8_MMA(ai, bj, At, Bt) do { __builtin_amdgcn_s_setprio(1); _Pragma("unroll") for (int m = 0; m < 4; ++m) _Pragma("unroll") for (int n = 0; n < 2; ++n) _Pragma("unroll") for (int k = 0; k < 2; ++k) \
;         acc[ai][bj][m][n] = __builtin_amdgcn_mfma_f32_16x16x32_bf16(Bt[n][k], At[m][k], acc[ai][bj][m][n], 0, 0, 0); __builtin_amdgcn_s_setprio(0); } while (0)
; #define PG8_WAIT_V(n) asm volatile("s_waitcnt vmcnt(" #n ")" ::: "memory")
; #define PG8_WAIT_L(n) asm volatile("s_waitcnt lgkmcnt(" #n ")" ::: "memory")
; #define PG8_BAR __builtin_amdgcn_s_barrier()
; #define PG8_SCHED __builtin_amdgcn_sched_barrier(0)
; template <class Epi, class Sched, int LD>
; __device__ __forceinline__ void gemm_phase(LAS unsigned char* lds, const Gemm g, const Sched& S, const Epi& E) {
;     ...
;             PG8_WAIT_V(6); PG8_BAR; PG8_MMA(1, 1, At, B1); PG8_BAR;
;             PG8_LDB(B0, 1, 0); PG8_SCHED; PG8_LDA(At, 1, 0); PG8_STAGE(PG8_SA(0, 1), a2 + hstep, voffA);
;             PG8_WAIT_L(8); PG8_BAR; PG8_WAIT_L(0); PG8_MMA(0, 0, At, B0); PG8_BAR; PG8_SCHED;
;             PG8_LDB(B1, 1, 1); PG8_STAGE(PG8_SB(1, 0), b3, voffB);
;             PG8_BAR; PG8_WAIT_L(0); PG8_MMA(0, 1, At, B1); PG8_BAR;
;             PG8_LDA(At, 1, 1); PG8_STAGE(PG8_SA(1, 0), a3, voffA);
	s_setprio 1
	v_mfma_f32_16x16x32_bf16 v[60:63], v[212:215], v[180:183], v[60:63]
	v_mfma_f32_16x16x32_bf16 v[52:55], v[220:223], v[180:183], v[52:55]
	v_mfma_f32_16x16x32_bf16 v[44:47], v[212:215], v[188:191], v[44:47]
	v_mfma_f32_16x16x32_bf16 v[36:39], v[220:223], v[188:191], v[36:39]
	v_mfma_f32_16x16x32_bf16 v[28:31], v[212:215], v[196:199], v[28:31]
	v_mfma_f32_16x16x32_bf16 v[20:23], v[220:223], v[196:199], v[20:23]
	v_mfma_f32_16x16x32_bf16 v[12:15], v[212:215], v[204:207], v[12:15]
	v_mfma_f32_16x16x32_bf16 v[4:7], v[220:223], v[204:207], v[4:7]
	v_mfma_f32_16x16x32_bf16 v[60:63], v[216:219], v[184:187], v[60:63]
	v_mfma_f32_16x16x32_bf16 v[52:55], v[224:227], v[184:187], v[52:55]
	v_mfma_f32_16x16x32_bf16 v[44:47], v[216:219], v[192:195], v[44:47]
	v_mfma_f32_16x16x32_bf16 v[36:39], v[224:227], v[192:195], v[36:39]
	v_mfma_f32_16x16x32_bf16 v[28:31], v[216:219], v[200:203], v[28:31]
	v_mfma_f32_16x16x32_bf16 v[20:23], v[224:227], v[200:203], v[20:23]
	s_setprio 2
	s_add_i32 s71, 0, 0x18000
	s_barrier
	v_mfma_f32_16x16x32_bf16 v[12:15], v[216:219], v[208:211], v[12:15]
	v_mfma_f32_16x16x32_bf16 v[4:7], v[224:227], v[208:211], v[4:7]
	s_setprio 0
	ds_read_b128 v[146:149], v228 offset:32768
	ds_read_b128 v[150:153], v228 offset:33792
	ds_read_b128 v[154:157], v228 offset:34816
	ds_read_b128 v[176:179], v228 offset:35840
	s_add_u32 s4, s4, 0x4000
	s_addc_u32 s5, s5, 0
	s_mov_b32 m0, s52
	ds_read_b128 v[180:183], v144 offset:32768
	ds_read_b128 v[184:187], v144 offset:33792
	ds_read_b128 v[188:191], v144 offset:34816
	ds_read_b128 v[192:195], v144 offset:35840
	ds_read_b128 v[196:199], v144 offset:36864
	ds_read_b128 v[200:203], v144 offset:37888
	ds_read_b128 v[204:207], v144 offset:38912
	ds_read_b128 v[208:211], v144 offset:39936
	global_load_lds_dwordx4 v138, s[4:5]
	s_mov_b32 m0, s53
	s_nop 0
	global_load_lds_dwordx4 v140, s[4:5]
	s_waitcnt lgkmcnt(8)
	s_barrier
	s_waitcnt lgkmcnt(0)
	s_setprio 1
	v_mfma_f32_16x16x32_bf16 v[128:131], v[146:149], v[180:183], v[128:131]
	v_mfma_f32_16x16x32_bf16 v[120:123], v[154:157], v[180:183], v[120:123]
	v_mfma_f32_16x16x32_bf16 v[112:115], v[146:149], v[188:191], v[112:115]
	v_mfma_f32_16x16x32_bf16 v[104:107], v[154:157], v[188:191], v[104:107]
	v_mfma_f32_16x16x32_bf16 v[96:99], v[146:149], v[196:199], v[96:99]
	v_mfma_f32_16x16x32_bf16 v[88:91], v[154:157], v[196:199], v[88:91]
	v_mfma_f32_16x16x32_bf16 v[80:83], v[146:149], v[204:207], v[80:83]
	v_mfma_f32_16x16x32_bf16 v[72:75], v[154:157], v[204:207], v[72:75]
	v_mfma_f32_16x16x32_bf16 v[128:131], v[150:153], v[184:187], v[128:131]
	v_mfma_f32_16x16x32_bf16 v[120:123], v[176:179], v[184:187], v[120:123]
	v_mfma_f32_16x16x32_bf16 v[112:115], v[150:153], v[192:195], v[112:115]
	v_mfma_f32_16x16x32_bf16 v[104:107], v[176:179], v[192:195], v[104:107]
	v_mfma_f32_16x16x32_bf16 v[96:99], v[150:153], v[200:203], v[96:99]
	v_mfma_f32_16x16x32_bf16 v[88:91], v[176:179], v[200:203], v[88:91]
	s_setprio 2
	s_barrier
	v_mfma_f32_16x16x32_bf16 v[80:83], v[150:153], v[208:211], v[80:83]
	v_mfma_f32_16x16x32_bf16 v[72:75], v[176:179], v[208:211], v[72:75]
	s_setprio 0
	s_add_i32 s72, 0, 0x1c000
	s_add_u32 s4, s54, 0x8000
	s_addc_u32 s5, s55, 0
	s_add_i32 s71, s71, s28
	s_mov_b32 m0, s71
	ds_read_b128 v[212:215], v228 offset:49152
	ds_read_b128 v[216:219], v228 offset:50176
	ds_read_b128 v[220:223], v228 offset:51200
	ds_read_b128 v[224:227], v228 offset:52224
	global_load_lds_dwordx4 v138, s[4:5]
	s_add_i32 m0, s71, 0x2000
	s_nop 0
	global_load_lds_dwordx4 v140, s[4:5]
	s_barrier
	s_waitcnt lgkmcnt(0)
	s_setprio 1
	v_mfma_f32_16x16x32_bf16 v[124:127], v[212:215], v[180:183], v[124:127]
	v_mfma_f32_16x16x32_bf16 v[116:119], v[220:223], v[180:183], v[116:119]
	v_mfma_f32_16x16x32_bf16 v[108:111], v[212:215], v[188:191], v[108:111]
	v_mfma_f32_16x16x32_bf16 v[100:103], v[220:223], v[188:191], v[100:103]
	v_mfma_f32_16x16x32_bf16 v[92:95], v[212:215], v[196:199], v[92:95]
	v_mfma_f32_16x16x32_bf16 v[84:87], v[220:223], v[196:199], v[84:87]
	v_mfma_f32_16x16x32_bf16 v[76:79], v[212:215], v[204:207], v[76:79]
	v_mfma_f32_16x16x32_bf16 v[68:71], v[220:223], v[204:207], v[68:71]
	v_mfma_f32_16x16x32_bf16 v[124:127], v[216:219], v[184:187], v[124:127]
	v_mfma_f32_16x16x32_bf16 v[116:119], v[224:227], v[184:187], v[116:119]
	v_mfma_f32_16x16x32_bf16 v[108:111], v[216:219], v[192:195], v[108:111]
	v_mfma_f32_16x16x32_bf16 v[100:103], v[224:227], v[192:195], v[100:103]
	v_mfma_f32_16x16x32_bf16 v[92:95], v[216:219], v[200:203], v[92:95]
	v_mfma_f32_16x16x32_bf16 v[84:87], v[224:227], v[200:203], v[84:87]
	s_setprio 2
	s_mov_b32 m0, s60
	s_barrier
	v_mfma_f32_16x16x32_bf16 v[76:79], v[216:219], v[208:211], v[76:79]
	v_mfma_f32_16x16x32_bf16 v[68:71], v[224:227], v[208:211], v[68:71]
	s_setprio 0
	ds_read_b128 v[180:183], v144 offset:49152
	ds_read_b128 v[184:187], v144 offset:50176
	ds_read_b128 v[188:191], v144 offset:51200
	ds_read_b128 v[192:195], v144 offset:52224
	ds_read_b128 v[196:199], v144 offset:53248
	ds_read_b128 v[200:203], v144 offset:54272
	ds_read_b128 v[204:207], v144 offset:55296
	ds_read_b128 v[208:211], v144 offset:56320
	global_load_lds_dwordx4 v138, s[56:57]
	s_mov_b32 m0, s61
	s_nop 0
	global_load_lds_dwordx4 v140, s[56:57]
	s_barrier
; __device__ __forceinline__ unsigned cvt_pk_bf16(float lo, float hi) { f32x2 v = {lo, hi}; bf16x2v b = __builtin_convertvector(v, bf16x2v); return __builtin_bit_cast(unsigned, b); }
; __device__ __forceinline__ float silu_f(float x) { return x * __builtin_amdgcn_rcpf(1.f + __expf(-x)); }
; #define PG8_STAGE(bufoff, gbase, voff) do { _Pragma("unroll") for (int _i = 0; _i < 2; ++_i) \
;         __builtin_amdgcn_global_load_lds((const unsigned*)((const char*)(gbase) + (voff)[_i]), (LAS unsigned*)(lds + (bufoff) + ldsw + _i * 8192), 16, 0, 0); } while (0)
; #define PG8_MMA(ai, bj, At, Bt) do { __builtin_amdgcn_s_setprio(1); _Pragma("unroll") for (int m = 0; m < 4; ++m) _Pragma("unroll") for (int n = 0; n < 2; ++n) _Pragma("unroll") for (int k = 0; k < 2; ++k) \
;         acc[ai][bj][m][n] = __builtin_amdgcn_mfma_f32_16x16x32_bf16(Bt[n][k], At[m][k], acc[ai][bj][m][n], 0, 0, 0); __builtin_amdgcn_s_setprio(0); } while (0)
; #define PG8_WAIT_V(n) asm volatile("s_waitcnt vmcnt(" #n ")" ::: "memory")
; #define PG8_WAIT_L(n) asm volatile("s_waitcnt lgkmcnt(" #n ")" ::: "memory")
;     __device__ __forceinline__ void operator()(const f32x4 (&acc)[2][2][4][2], const Unit& u, int wr, int wc, int fr, int fq) const {
;         const int row0 = u.pm * BM + wr * 64 + fr, col0 = u.pn * 128 + wc * 32 + 8 * fq;
; #pragma unroll
;         for (int ai = 0; ai < 2; ++ai)
; #pragma unroll
;             for (int m = 0; m < 4; ++m) {
;                 bf16_t* rowp = O + img_off(row0 + ai * HALF + m * 16, col0, D_FF / 64);
;                 const f32x4 g0 = acc[ai][0][m][0], g1 = acc[ai][0][m][1], u0 = acc[ai][1][m][0], u1 = acc[ai][1][m][1];
;                 u32x4 w;
;                 w.x = cvt_pk_bf16(silu_f(g0[0]) * u0[0], silu_f(g0[1]) * u0[1]); w.y = cvt_pk_bf16(silu_f(g0[2]) * u0[2], silu_f(g0[3]) * u0[3]);
;                 w.z = cvt_pk_bf16(silu_f(g1[0]) * u1[0], silu_f(g1[1]) * u1[1]); w.w = cvt_pk_bf16(silu_f(g1[2]) * u1[2], silu_f(g1[3]) * u1[3]);
;                 *(u32x4*)rowp = w;
; template <class Epi, class Sched, int LD>
; __device__ __forceinline__ void gemm_phase(LAS unsigned char* lds, const Gemm g, const Sched& S, const Epi& E) {
;     ...
;             PG8_BAR; PG8_WAIT_L(0); PG8_MMA(1, 0, At, B0); PG8_BAR; PG8_SCHED;
;             PG8_STAGE(PG8_SB(1, 1), b3 + hstep, voffB);
;             PG8_WAIT_V(6); PG8_BAR; PG8_MMA(1, 1, At, B1); PG8_BAR;
	s_waitcnt lgkmcnt(0)
	s_setprio 1
	v_mfma_f32_16x16x32_bf16 v[64:67], v[146:149], v[180:183], v[64:67]
	v_mfma_f32_16x16x32_bf16 v[56:59], v[154:157], v[180:183], v[56:59]
	v_mfma_f32_16x16x32_bf16 v[48:51], v[146:149], v[188:191], v[48:51]
	v_mfma_f32_16x16x32_bf16 v[40:43], v[154:157], v[188:191], v[40:43]
	v_mfma_f32_16x16x32_bf16 v[32:35], v[146:149], v[196:199], v[32:35]
	v_mfma_f32_16x16x32_bf16 v[24:27], v[154:157], v[196:199], v[24:27]
	v_mfma_f32_16x16x32_bf16 v[16:19], v[146:149], v[204:207], v[16:19]
	v_mfma_f32_16x16x32_bf16 v[8:11], v[154:157], v[204:207], v[8:11]
	v_mfma_f32_16x16x32_bf16 v[64:67], v[150:153], v[184:187], v[64:67]
	v_mfma_f32_16x16x32_bf16 v[56:59], v[176:179], v[184:187], v[56:59]
	v_mfma_f32_16x16x32_bf16 v[48:51], v[150:153], v[192:195], v[48:51]
	v_mfma_f32_16x16x32_bf16 v[40:43], v[176:179], v[192:195], v[40:43]
	v_mfma_f32_16x16x32_bf16 v[32:35], v[150:153], v[200:203], v[32:35]
	v_mfma_f32_16x16x32_bf16 v[24:27], v[176:179], v[200:203], v[24:27]
	s_setprio 2
	s_barrier
	v_mfma_f32_16x16x32_bf16 v[16:19], v[150:153], v[208:211], v[16:19]
	v_mfma_f32_16x16x32_bf16 v[8:11], v[176:179], v[208:211], v[8:11]
	s_setprio 0
	s_add_u32 s4, s54, 0xc000
	s_addc_u32 s5, s55, 0
	s_add_i32 s54, s72, s28
	s_mov_b32 m0, s54
	s_nop 0
	global_load_lds_dwordx4 v138, s[4:5]
	s_add_i32 m0, s54, 0x2000
	s_nop 0
	global_load_lds_dwordx4 v140, s[4:5]
	s_waitcnt vmcnt(6)
	s_barrier
	s_setprio 1
	v_mfma_f32_16x16x32_bf16 v[60:63], v[212:215], v[180:183], v[60:63]
	v_mfma_f32_16x16x32_bf16 v[52:55], v[220:223], v[180:183], v[52:55]
	v_mfma_f32_16x16x32_bf16 v[44:47], v[212:215], v[188:191], v[44:47]
	v_mfma_f32_16x16x32_bf16 v[36:39], v[220:223], v[188:191], v[36:39]
	v_mfma_f32_16x16x32_bf16 v[28:31], v[212:215], v[196:199], v[28:31]
	v_mfma_f32_16x16x32_bf16 v[20:23], v[220:223], v[196:199], v[20:23]
	v_mfma_f32_16x16x32_bf16 v[12:15], v[212:215], v[204:207], v[12:15]
	v_mfma_f32_16x16x32_bf16 v[4:7], v[220:223], v[204:207], v[4:7]
	v_mfma_f32_16x16x32_bf16 v[60:63], v[216:219], v[184:187], v[60:63]
	v_mfma_f32_16x16x32_bf16 v[52:55], v[224:227], v[184:187], v[52:55]
	v_mfma_f32_16x16x32_bf16 v[44:47], v[216:219], v[192:195], v[44:47]
	v_mfma_f32_16x16x32_bf16 v[36:39], v[224:227], v[192:195], v[36:39]
	v_mfma_f32_16x16x32_bf16 v[28:31], v[216:219], v[200:203], v[28:31]
	v_mfma_f32_16x16x32_bf16 v[20:23], v[224:227], v[200:203], v[20:23]
	s_setprio 2
	s_add_i32 s70, s70, 2
	s_add_u32 s50, s50, 0x10000
	s_addc_u32 s51, s51, 0
	s_add_u32 s45, s45, 0x10000
	s_addc_u32 s47, s47, 0
	s_cmp_gt_u32 s70, 29
	s_barrier
	v_mfma_f32_16x16x32_bf16 v[12:15], v[216:219], v[208:211], v[12:15]
	v_mfma_f32_16x16x32_bf16 v[4:7], v[224:227], v[208:211], v[4:7]
	s_setprio 0
	s_cbranch_scc0 .LBB0_899
	v_mul_f32_e32 v148, 0xbfb8aa3b, v128
	v_mul_f32_e32 v149, 0xbfb8aa3b, v129
	v_exp_f32_e32 v148, v148
	v_exp_f32_e32 v149, v149
	s_lshl_b32 s5, s69, 8
	s_add_i32 s5, s5, s58
	v_add_f32_e32 v148, 1.0, v148
	v_add_f32_e32 v149, 1.0, v149
	v_rcp_f32_e32 v148, v148
	v_rcp_f32_e32 v149, v149
	s_lshl_b32 s4, s68, 7
	s_or_b32 s4, s4, s59
	s_ashr_i32 s45, s5, 8
	v_pk_mul_f32 v[128:129], v[128:129], v[148:149]
	s_ashr_i32 s4, s4, 6
	v_pk_mul_f32 v[124:125], v[128:129], v[124:125]
	s_mulk_i32 s45, 0x58
	v_cvt_pk_bf16_f32 v124, v124, v125
	v_mul_f32_e32 v125, 0xbfb8aa3b, v130
	v_exp_f32_e32 v125, v125
	s_add_i32 s50, s45, s4
	s_ashr_i32 s51, s50, 31
	s_lshl_b64 s[50:51], s[50:51], 15
	v_add_f32_e32 v125, 1.0, v125
	v_rcp_f32_e32 v128, v125
	v_mul_f32_e32 v125, 0xbfb8aa3b, v131
	v_exp_f32_e32 v125, v125
	s_add_u32 s45, s16, s50
	s_addc_u32 s47, s17, s51
	s_lshl_b32 s50, s5, 7
	v_add_f32_e32 v125, 1.0, v125
	v_rcp_f32_e32 v129, v125
	s_and_b32 s50, s50, 0x4000
	s_add_u32 s50, s45, s50
	s_addc_u32 s51, s47, 0
	v_pk_mul_f32 v[128:129], v[130:131], v[128:129]
	s_or_b32 s45, s5, 16
	v_pk_mul_f32 v[126:127], v[128:129], v[126:127]
	s_lshr_b32 s45, s45, 3
	v_cvt_pk_bf16_f32 v125, v126, v127
	v_mul_f32_e32 v126, 0xbfb8aa3b, v120
	v_mul_f32_e32 v127, 0xbfb8aa3b, v121
	v_exp_f32_e32 v126, v126
	v_exp_f32_e32 v127, v127
	v_or_b32_e32 v145, s5, v137
	s_and_b32 s45, s45, 10
	v_add_f32_e32 v126, 1.0, v126
	v_add_f32_e32 v127, 1.0, v127
	v_rcp_f32_e32 v126, v126
	v_rcp_f32_e32 v127, v127
	v_lshlrev_b32_e32 v132, 6, v145
	v_lshlrev_b32_e32 v146, 2, v145
	s_or_b32 s45, s45, s64
	v_pk_mul_f32 v[120:121], v[120:121], v[126:127]
	v_and_or_b32 v132, v132, s15, v142
	v_pk_mul_f32 v[116:117], v[120:121], v[116:117]
	v_and_b32_e32 v146, 32, v146
	v_cvt_pk_bf16_f32 v126, v116, v117
	v_mul_f32_e32 v116, 0xbfb8aa3b, v122
	v_mul_f32_e32 v117, 0xbfb8aa3b, v123
	v_exp_f32_e32 v116, v116
	v_exp_f32_e32 v117, v117
	s_lshl_b32 s45, s45, 10
	v_bitop3_b32 v147, v132, s65, v146 bitop3:0xde
	v_add_f32_e32 v116, 1.0, v116
	v_add_f32_e32 v117, 1.0, v117
	v_rcp_f32_e32 v116, v116
	v_rcp_f32_e32 v117, v117
	s_and_b64 vcc, exec, s[42:43]
	s_mov_b32 s68, s44
	s_mov_b32 s69, s46
	v_pk_mul_f32 v[116:117], v[122:123], v[116:117]
	s_mov_b64 s[54:55], s[40:41]
	v_pk_mul_f32 v[116:117], v[116:117], v[118:119]
	v_bitop3_b32 v118, v132, s45, v146 bitop3:0xde
	v_cvt_pk_bf16_f32 v127, v116, v117
	v_mul_f32_e32 v116, 0xbfb8aa3b, v112
	v_mul_f32_e32 v117, 0xbfb8aa3b, v113
	v_exp_f32_e32 v116, v116
	v_exp_f32_e32 v117, v117
	s_or_b32 s45, s5, 32
	s_or_b32 s5, s5, 48
	v_add_f32_e32 v116, 1.0, v116
	v_add_f32_e32 v117, 1.0, v117
	v_rcp_f32_e32 v116, v116
	v_rcp_f32_e32 v117, v117
	s_lshr_b32 s45, s45, 3
	s_lshr_b32 s5, s5, 3
	s_and_b32 s45, s45, 12
	v_pk_mul_f32 v[112:113], v[112:113], v[116:117]
	s_and_b32 s5, s5, 14
	v_pk_mul_f32 v[108:109], v[112:113], v[108:109]
	s_or_b32 s45, s45, s64
	v_cvt_pk_bf16_f32 v108, v108, v109
; __device__ __forceinline__ unsigned cvt_pk_bf16(float lo, float hi) { f32x2 v = {lo, hi}; bf16x2v b = __builtin_convertvector(v, bf16x2v); return __builtin_bit_cast(unsigned, b); }
; __device__ __forceinline__ float silu_f(float x) { return x * __builtin_amdgcn_rcpf(1.f + __expf(-x)); }
;     __device__ __forceinline__ void operator()(const f32x4 (&acc)[2][2][4][2], const Unit& u, int wr, int wc, int fr, int fq) const {
;         const int row0 = u.pm * BM + wr * 64 + fr, col0 = u.pn * 128 + wc * 32 + 8 * fq;
; #pragma unroll
;         for (int ai = 0; ai < 2; ++ai)
; #pragma unroll
;             for (int m = 0; m < 4; ++m) {
;                 bf16_t* rowp = O + img_off(row0 + ai * HALF + m * 16, col0, D_FF / 64);
;                 const f32x4 g0 = acc[ai][0][m][0], g1 = acc[ai][0][m][1], u0 = acc[ai][1][m][0], u1 = acc[ai][1][m][1];
;                 u32x4 w;
;                 w.x = cvt_pk_bf16(silu_f(g0[0]) * u0[0], silu_f(g0[1]) * u0[1]); w.y = cvt_pk_bf16(silu_f(g0[2]) * u0[2], silu_f(g0[3]) * u0[3]);
;                 w.z = cvt_pk_bf16(silu_f(g1[0]) * u1[0], silu_f(g1[1]) * u1[1]); w.w = cvt_pk_bf16(silu_f(g1[2]) * u1[2], silu_f(g1[3]) * u1[3]);
;                 *(u32x4*)rowp = w;
	v_mul_f32_e32 v109, 0xbfb8aa3b, v114
	v_exp_f32_e32 v109, v109
	s_or_b32 s5, s5, s64
	s_lshl_b32 s45, s45, 10
	s_lshl_b32 s5, s5, 10
	v_add_f32_e32 v109, 1.0, v109
	v_rcp_f32_e32 v112, v109
	v_mul_f32_e32 v109, 0xbfb8aa3b, v115
	v_exp_f32_e32 v109, v109
	global_store_dwordx4 v147, v[124:127], s[50:51]
	v_add_f32_e32 v109, 1.0, v109
	v_rcp_f32_e32 v113, v109
	s_nop 0
	v_pk_mul_f32 v[112:113], v[114:115], v[112:113]
	s_nop 0
	v_pk_mul_f32 v[110:111], v[112:113], v[110:111]
	s_nop 0
	v_cvt_pk_bf16_f32 v109, v110, v111
	v_mul_f32_e32 v110, 0xbfb8aa3b, v104
	v_mul_f32_e32 v111, 0xbfb8aa3b, v105
	v_exp_f32_e32 v110, v110
	v_exp_f32_e32 v111, v111
	v_add_f32_e32 v110, 1.0, v110
	v_add_f32_e32 v111, 1.0, v111
	v_rcp_f32_e32 v110, v110
	v_rcp_f32_e32 v111, v111
	s_nop 0
	v_pk_mul_f32 v[104:105], v[104:105], v[110:111]
	s_nop 0
	v_pk_mul_f32 v[100:101], v[104:105], v[100:101]
	s_nop 0
	v_cvt_pk_bf16_f32 v110, v100, v101
	v_mul_f32_e32 v100, 0xbfb8aa3b, v106
	v_mul_f32_e32 v101, 0xbfb8aa3b, v107
	v_exp_f32_e32 v100, v100
	v_exp_f32_e32 v101, v101
	v_add_f32_e32 v100, 1.0, v100
	v_add_f32_e32 v101, 1.0, v101
	v_rcp_f32_e32 v100, v100
	v_rcp_f32_e32 v101, v101
	s_nop 0
	v_pk_mul_f32 v[100:101], v[106:107], v[100:101]
	s_nop 0
	v_pk_mul_f32 v[100:101], v[100:101], v[102:103]
	v_bitop3_b32 v102, v132, s45, v146 bitop3:0xde
	v_cvt_pk_bf16_f32 v111, v100, v101
	v_mul_f32_e32 v100, 0xbfb8aa3b, v96
	v_mul_f32_e32 v101, 0xbfb8aa3b, v97
	v_exp_f32_e32 v100, v100
	v_exp_f32_e32 v101, v101
	global_store_dwordx4 v118, v[108:111], s[50:51]
	v_add_f32_e32 v100, 1.0, v100
	v_add_f32_e32 v101, 1.0, v101
	v_rcp_f32_e32 v100, v100
	v_rcp_f32_e32 v101, v101
	s_nop 0
	v_pk_mul_f32 v[96:97], v[96:97], v[100:101]
	s_nop 0
	v_pk_mul_f32 v[92:93], v[96:97], v[92:93]
	s_nop 0
	v_cvt_pk_bf16_f32 v92, v92, v93
	v_mul_f32_e32 v93, 0xbfb8aa3b, v98
	v_exp_f32_e32 v93, v93
	s_nop 0
	v_add_f32_e32 v93, 1.0, v93
	v_rcp_f32_e32 v96, v93
	v_mul_f32_e32 v93, 0xbfb8aa3b, v99
	v_exp_f32_e32 v93, v93
	s_nop 0
	v_add_f32_e32 v93, 1.0, v93
	v_rcp_f32_e32 v97, v93
	s_nop 0
	v_pk_mul_f32 v[96:97], v[98:99], v[96:97]
	s_nop 0
	v_pk_mul_f32 v[94:95], v[96:97], v[94:95]
	s_nop 0
	v_cvt_pk_bf16_f32 v93, v94, v95
	v_mul_f32_e32 v94, 0xbfb8aa3b, v88
	v_mul_f32_e32 v95, 0xbfb8aa3b, v89
	v_exp_f32_e32 v94, v94
	v_exp_f32_e32 v95, v95
	v_add_f32_e32 v94, 1.0, v94
	v_add_f32_e32 v95, 1.0, v95
	v_rcp_f32_e32 v94, v94
	v_rcp_f32_e32 v95, v95
	s_nop 0
	v_pk_mul_f32 v[88:89], v[88:89], v[94:95]
	s_nop 0
	v_pk_mul_f32 v[84:85], v[88:89], v[84:85]
	s_nop 0
	v_cvt_pk_bf16_f32 v94, v84, v85
	v_mul_f32_e32 v84, 0xbfb8aa3b, v90
	v_mul_f32_e32 v85, 0xbfb8aa3b, v91
	v_exp_f32_e32 v84, v84
	v_exp_f32_e32 v85, v85
	v_add_f32_e32 v84, 1.0, v84
	v_add_f32_e32 v85, 1.0, v85
	v_rcp_f32_e32 v84, v84
	v_rcp_f32_e32 v85, v85
	s_nop 0
	v_pk_mul_f32 v[84:85], v[90:91], v[84:85]
	s_nop 0
	v_pk_mul_f32 v[84:85], v[84:85], v[86:87]
	v_bitop3_b32 v86, v132, s5, v146 bitop3:0xde
	v_cvt_pk_bf16_f32 v95, v84, v85
	v_mul_f32_e32 v84, 0xbfb8aa3b, v80
	v_mul_f32_e32 v85, 0xbfb8aa3b, v81
	v_exp_f32_e32 v84, v84
	v_exp_f32_e32 v85, v85
	global_store_dwordx4 v102, v[92:95], s[50:51]
	v_add_f32_e32 v84, 1.0, v84
	v_add_f32_e32 v85, 1.0, v85
	v_rcp_f32_e32 v84, v84
	v_rcp_f32_e32 v85, v85
	s_nop 0
	v_pk_mul_f32 v[80:81], v[80:81], v[84:85]
	s_nop 0
	v_pk_mul_f32 v[76:77], v[80:81], v[76:77]
	s_nop 0
	v_cvt_pk_bf16_f32 v76, v76, v77
	v_mul_f32_e32 v77, 0xbfb8aa3b, v82
	v_exp_f32_e32 v77, v77
	s_nop 0
	v_add_f32_e32 v77, 1.0, v77
	v_rcp_f32_e32 v80, v77
	v_mul_f32_e32 v77, 0xbfb8aa3b, v83
	v_exp_f32_e32 v77, v77
	s_nop 0
	v_add_f32_e32 v77, 1.0, v77
	v_rcp_f32_e32 v81, v77
	s_nop 0
	v_pk_mul_f32 v[80:81], v[82:83], v[80:81]
	s_nop 0
	v_pk_mul_f32 v[78:79], v[80:81], v[78:79]
	s_nop 0
	v_cvt_pk_bf16_f32 v77, v78, v79
	v_mul_f32_e32 v78, 0xbfb8aa3b, v72
	v_mul_f32_e32 v79, 0xbfb8aa3b, v73
	v_exp_f32_e32 v78, v78
	v_exp_f32_e32 v79, v79
	v_add_f32_e32 v78, 1.0, v78
	v_add_f32_e32 v79, 1.0, v79
	v_rcp_f32_e32 v78, v78
	v_rcp_f32_e32 v79, v79
	s_nop 0
	v_pk_mul_f32 v[72:73], v[72:73], v[78:79]
	s_nop 0
	v_pk_mul_f32 v[68:69], v[72:73], v[68:69]
	v_mul_f32_e32 v73, 0xbfb8aa3b, v65
	v_cvt_pk_bf16_f32 v78, v68, v69
	v_mul_f32_e32 v68, 0xbfb8aa3b, v74
	v_mul_f32_e32 v69, 0xbfb8aa3b, v75
	v_exp_f32_e32 v68, v68
	v_exp_f32_e32 v69, v69
	v_exp_f32_e32 v73, v73
	v_add_f32_e32 v68, 1.0, v68
	v_add_f32_e32 v69, 1.0, v69
	v_rcp_f32_e32 v68, v68
	v_rcp_f32_e32 v69, v69
	v_add_f32_e32 v73, 1.0, v73
	v_rcp_f32_e32 v73, v73
	v_pk_mul_f32 v[68:69], v[74:75], v[68:69]
	s_nop 0
	v_pk_mul_f32 v[68:69], v[68:69], v[70:71]
	v_add_u32_e32 v70, 0x80, v145
	v_lshlrev_b32_e32 v71, 6, v70
	v_lshlrev_b32_e32 v72, 2, v70
	v_and_or_b32 v71, v71, s15, v142
	v_and_b32_e32 v72, 32, v72
	v_bitop3_b32 v132, v71, s65, v72 bitop3:0xde
	v_mul_f32_e32 v72, 0xbfb8aa3b, v64
	v_exp_f32_e32 v72, v72
	v_cvt_pk_bf16_f32 v79, v68, v69
	v_lshrrev_b32_e32 v68, 8, v70
	v_mov_b32_e32 v69, s4
	v_add_f32_e32 v72, 1.0, v72
	v_rcp_f32_e32 v72, v72
	s_movk_i32 s4, 0x58
	v_mad_i32_i24 v68, v68, s4, v69
	v_ashrrev_i32_e32 v69, 31, v68
	v_pk_mul_f32 v[64:65], v[64:65], v[72:73]
	v_lshlrev_b64 v[68:69], 15, v[68:69]
	v_pk_mul_f32 v[60:61], v[64:65], v[60:61]
	v_lshlrev_b32_e32 v70, 7, v70
	v_cvt_pk_bf16_f32 v60, v60, v61
	v_mul_f32_e32 v61, 0xbfb8aa3b, v66
	v_exp_f32_e32 v61, v61
	v_lshl_add_u64 v[68:69], s[16:17], 0, v[68:69]
	v_and_b32_e32 v70, 0x4000, v70
	v_mov_b32_e32 v71, v133
	v_add_f32_e32 v61, 1.0, v61
	v_rcp_f32_e32 v64, v61
	v_mul_f32_e32 v61, 0xbfb8aa3b, v67
	v_exp_f32_e32 v61, v61
	v_lshl_add_u64 v[70:71], v[68:69], 0, v[70:71]
	v_lshl_add_u64 v[70:71], v[70:71], 0, v[132:133]
; __device__ __forceinline__ unsigned cvt_pk_bf16(float lo, float hi) { f32x2 v = {lo, hi}; bf16x2v b = __builtin_convertvector(v, bf16x2v); return __builtin_bit_cast(unsigned, b); }
; __device__ __forceinline__ float silu_f(float x) { return x * __builtin_amdgcn_rcpf(1.f + __expf(-x)); }
;     __device__ __forceinline__ void operator()(const f32x4 (&acc)[2][2][4][2], const Unit& u, int wr, int wc, int fr, int fq) const {
;         const int row0 = u.pm * BM + wr * 64 + fr, col0 = u.pn * 128 + wc * 32 + 8 * fq;
; #pragma unroll
;         for (int ai = 0; ai < 2; ++ai)
; #pragma unroll
;             for (int m = 0; m < 4; ++m) {
;                 bf16_t* rowp = O + img_off(row0 + ai * HALF + m * 16, col0, D_FF / 64);
;                 const f32x4 g0 = acc[ai][0][m][0], g1 = acc[ai][0][m][1], u0 = acc[ai][1][m][0], u1 = acc[ai][1][m][1];
;                 u32x4 w;
;                 w.x = cvt_pk_bf16(silu_f(g0[0]) * u0[0], silu_f(g0[1]) * u0[1]); w.y = cvt_pk_bf16(silu_f(g0[2]) * u0[2], silu_f(g0[3]) * u0[3]);
;                 w.z = cvt_pk_bf16(silu_f(g1[0]) * u1[0], silu_f(g1[1]) * u1[1]); w.w = cvt_pk_bf16(silu_f(g1[2]) * u1[2], silu_f(g1[3]) * u1[3]);
;                 *(u32x4*)rowp = w;
	s_mov_b64 s[4:5], s[48:49]
	v_add_f32_e32 v61, 1.0, v61
	v_rcp_f32_e32 v65, v61
	global_store_dwordx4 v86, v[76:79], s[50:51]
	v_pk_mul_f32 v[64:65], v[66:67], v[64:65]
	s_nop 0
	v_pk_mul_f32 v[62:63], v[64:65], v[62:63]
	s_nop 0
	v_cvt_pk_bf16_f32 v61, v62, v63
	v_mul_f32_e32 v62, 0xbfb8aa3b, v56
	v_mul_f32_e32 v63, 0xbfb8aa3b, v57
	v_exp_f32_e32 v62, v62
	v_exp_f32_e32 v63, v63
	v_add_f32_e32 v62, 1.0, v62
	v_add_f32_e32 v63, 1.0, v63
	v_rcp_f32_e32 v62, v62
	v_rcp_f32_e32 v63, v63
	s_nop 0
	v_pk_mul_f32 v[56:57], v[56:57], v[62:63]
	s_nop 0
	v_pk_mul_f32 v[52:53], v[56:57], v[52:53]
	s_nop 0
	v_cvt_pk_bf16_f32 v62, v52, v53
	v_mul_f32_e32 v52, 0xbfb8aa3b, v58
	v_mul_f32_e32 v53, 0xbfb8aa3b, v59
	v_exp_f32_e32 v52, v52
	v_exp_f32_e32 v53, v53
	v_add_f32_e32 v52, 1.0, v52
	v_add_f32_e32 v53, 1.0, v53
	v_rcp_f32_e32 v52, v52
	v_rcp_f32_e32 v53, v53
	s_nop 0
	v_pk_mul_f32 v[52:53], v[58:59], v[52:53]
	s_nop 0
	v_pk_mul_f32 v[52:53], v[52:53], v[54:55]
	s_nop 0
	v_cvt_pk_bf16_f32 v63, v52, v53
	v_add_u32_e32 v52, 0x90, v145
	v_lshrrev_b32_e32 v54, 3, v52
	v_lshlrev_b32_e32 v53, 6, v52
	v_and_or_b32 v54, v54, 10, s64
	v_lshlrev_b32_e32 v55, 2, v52
	v_and_or_b32 v53, v53, s15, v142
	v_lshlrev_b32_e32 v54, 10, v54
	v_and_b32_e32 v55, 32, v55
	v_bitop3_b32 v132, v53, v54, v55 bitop3:0xde
	v_mul_f32_e32 v54, 0xbfb8aa3b, v48
	v_mul_f32_e32 v55, 0xbfb8aa3b, v49
	v_exp_f32_e32 v54, v54
	v_exp_f32_e32 v55, v55
	v_lshlrev_b32_e32 v52, 7, v52
	v_and_b32_e32 v52, 0x4000, v52
	v_add_f32_e32 v54, 1.0, v54
	v_add_f32_e32 v55, 1.0, v55
	v_rcp_f32_e32 v54, v54
	v_rcp_f32_e32 v55, v55
	v_mov_b32_e32 v53, v133
	v_lshl_add_u64 v[52:53], v[68:69], 0, v[52:53]
	v_lshl_add_u64 v[52:53], v[52:53], 0, v[132:133]
	v_pk_mul_f32 v[48:49], v[48:49], v[54:55]
	global_store_dwordx4 v[70:71], v[60:63], off
	v_pk_mul_f32 v[44:45], v[48:49], v[44:45]
	s_nop 0
	v_cvt_pk_bf16_f32 v44, v44, v45
	v_mul_f32_e32 v45, 0xbfb8aa3b, v50
	v_exp_f32_e32 v45, v45
	s_nop 0
	v_add_f32_e32 v45, 1.0, v45
	v_rcp_f32_e32 v48, v45
	v_mul_f32_e32 v45, 0xbfb8aa3b, v51
	v_exp_f32_e32 v45, v45
	s_nop 0
	v_add_f32_e32 v45, 1.0, v45
	v_rcp_f32_e32 v49, v45
	s_nop 0
	v_pk_mul_f32 v[48:49], v[50:51], v[48:49]
	s_nop 0
	v_pk_mul_f32 v[46:47], v[48:49], v[46:47]
	s_nop 0
	v_cvt_pk_bf16_f32 v45, v46, v47
	v_mul_f32_e32 v46, 0xbfb8aa3b, v40
	v_mul_f32_e32 v47, 0xbfb8aa3b, v41
	v_exp_f32_e32 v46, v46
	v_exp_f32_e32 v47, v47
	v_add_f32_e32 v46, 1.0, v46
	v_add_f32_e32 v47, 1.0, v47
	v_rcp_f32_e32 v46, v46
	v_rcp_f32_e32 v47, v47
	s_nop 0
	v_pk_mul_f32 v[40:41], v[40:41], v[46:47]
	s_nop 0
	v_pk_mul_f32 v[36:37], v[40:41], v[36:37]
	s_nop 0
	v_cvt_pk_bf16_f32 v46, v36, v37
	v_mul_f32_e32 v36, 0xbfb8aa3b, v42
	v_mul_f32_e32 v37, 0xbfb8aa3b, v43
	v_exp_f32_e32 v36, v36
	v_exp_f32_e32 v37, v37
	v_add_f32_e32 v36, 1.0, v36
	v_add_f32_e32 v37, 1.0, v37
	v_rcp_f32_e32 v36, v36
	v_rcp_f32_e32 v37, v37
	s_nop 0
	v_pk_mul_f32 v[36:37], v[42:43], v[36:37]
	s_nop 0
	v_pk_mul_f32 v[36:37], v[36:37], v[38:39]
	s_nop 0
	v_cvt_pk_bf16_f32 v47, v36, v37
	v_add_u32_e32 v36, 0xa0, v145
	v_lshrrev_b32_e32 v38, 3, v36
	v_lshlrev_b32_e32 v37, 6, v36
	v_and_or_b32 v38, v38, 12, s64
	v_lshlrev_b32_e32 v39, 2, v36
	v_and_or_b32 v37, v37, s15, v142
	v_lshlrev_b32_e32 v38, 10, v38
	v_and_b32_e32 v39, 32, v39
	v_bitop3_b32 v132, v37, v38, v39 bitop3:0xde
	v_mul_f32_e32 v38, 0xbfb8aa3b, v32
	v_mul_f32_e32 v39, 0xbfb8aa3b, v33
	v_exp_f32_e32 v38, v38
	v_exp_f32_e32 v39, v39
	v_lshlrev_b32_e32 v36, 7, v36
	v_and_b32_e32 v36, 0x4000, v36
	v_add_f32_e32 v38, 1.0, v38
	v_add_f32_e32 v39, 1.0, v39
	v_rcp_f32_e32 v38, v38
; __device__ __forceinline__ unsigned cvt_pk_bf16(float lo, float hi) { f32x2 v = {lo, hi}; bf16x2v b = __builtin_convertvector(v, bf16x2v); return __builtin_bit_cast(unsigned, b); }
; __device__ __forceinline__ float silu_f(float x) { return x * __builtin_amdgcn_rcpf(1.f + __expf(-x)); }
; #define PG8_WAIT_V(n) asm volatile("s_waitcnt vmcnt(" #n ")" ::: "memory")
; #define PG8_BAR __builtin_amdgcn_s_barrier()
;     __device__ __forceinline__ void operator()(const f32x4 (&acc)[2][2][4][2], const Unit& u, int wr, int wc, int fr, int fq) const {
;         const int row0 = u.pm * BM + wr * 64 + fr, col0 = u.pn * 128 + wc * 32 + 8 * fq;
; #pragma unroll
;         for (int ai = 0; ai < 2; ++ai)
; #pragma unroll
;             for (int m = 0; m < 4; ++m) {
;                 bf16_t* rowp = O + img_off(row0 + ai * HALF + m * 16, col0, D_FF / 64);
;                 const f32x4 g0 = acc[ai][0][m][0], g1 = acc[ai][0][m][1], u0 = acc[ai][1][m][0], u1 = acc[ai][1][m][1];
;                 u32x4 w;
;                 w.x = cvt_pk_bf16(silu_f(g0[0]) * u0[0], silu_f(g0[1]) * u0[1]); w.y = cvt_pk_bf16(silu_f(g0[2]) * u0[2], silu_f(g0[3]) * u0[3]);
;                 w.z = cvt_pk_bf16(silu_f(g1[0]) * u1[0], silu_f(g1[1]) * u1[1]); w.w = cvt_pk_bf16(silu_f(g1[2]) * u1[2], silu_f(g1[3]) * u1[3]);
;                 *(u32x4*)rowp = w;
; template <class Epi, class Sched, int LD>
; __device__ __forceinline__ void gemm_phase(LAS unsigned char* lds, const Gemm g, const Sched& S, const Epi& E) {
;     ...
;         E(acc, cur, wr, wc, fr, fq);
;         if (!has_next) break;
; #pragma unroll
;         for (int a = 0; a < 2; ++a)
; #pragma unroll
;             for (int b = 0; b < 2; ++b)
; #pragma unroll
;                 for (int m = 0; m < 4; ++m)
; #pragma unroll
;                     for (int n = 0; n < 2; ++n) acc[a][b][m][n] = (f32x4){0.f, 0.f, 0.f, 0.f};
;         cur = nxt; cA = nA; cB = nB; ++ui;
;     }
;     PG8_WAIT_V(0);
;     if (wr == 0) PG8_BAR;
;     PG8_BAR;
	v_rcp_f32_e32 v39, v39
	v_mov_b32_e32 v37, v133
	v_lshl_add_u64 v[36:37], v[68:69], 0, v[36:37]
	v_lshl_add_u64 v[36:37], v[36:37], 0, v[132:133]
	v_pk_mul_f32 v[32:33], v[32:33], v[38:39]
	global_store_dwordx4 v[52:53], v[44:47], off
	v_pk_mul_f32 v[28:29], v[32:33], v[28:29]
	s_nop 0
	v_cvt_pk_bf16_f32 v28, v28, v29
	v_mul_f32_e32 v29, 0xbfb8aa3b, v34
	v_exp_f32_e32 v29, v29
	s_nop 0
	v_add_f32_e32 v29, 1.0, v29
	v_rcp_f32_e32 v32, v29
	v_mul_f32_e32 v29, 0xbfb8aa3b, v35
	v_exp_f32_e32 v29, v29
	s_nop 0
	v_add_f32_e32 v29, 1.0, v29
	v_rcp_f32_e32 v33, v29
	s_nop 0
	v_pk_mul_f32 v[32:33], v[34:35], v[32:33]
	s_nop 0
	v_pk_mul_f32 v[30:31], v[32:33], v[30:31]
	s_nop 0
	v_cvt_pk_bf16_f32 v29, v30, v31
	v_mul_f32_e32 v30, 0xbfb8aa3b, v24
	v_mul_f32_e32 v31, 0xbfb8aa3b, v25
	v_exp_f32_e32 v30, v30
	v_exp_f32_e32 v31, v31
	v_add_f32_e32 v30, 1.0, v30
	v_add_f32_e32 v31, 1.0, v31
	v_rcp_f32_e32 v30, v30
	v_rcp_f32_e32 v31, v31
	s_nop 0
	v_pk_mul_f32 v[24:25], v[24:25], v[30:31]
	s_nop 0
	v_pk_mul_f32 v[20:21], v[24:25], v[20:21]
	s_nop 0
	v_cvt_pk_bf16_f32 v30, v20, v21
	v_mul_f32_e32 v20, 0xbfb8aa3b, v26
	v_mul_f32_e32 v21, 0xbfb8aa3b, v27
	v_exp_f32_e32 v20, v20
	v_exp_f32_e32 v21, v21
	v_add_f32_e32 v20, 1.0, v20
	v_add_f32_e32 v21, 1.0, v21
	v_rcp_f32_e32 v20, v20
	v_rcp_f32_e32 v21, v21
	s_nop 0
	v_pk_mul_f32 v[20:21], v[26:27], v[20:21]
	s_nop 0
	v_pk_mul_f32 v[20:21], v[20:21], v[22:23]
	s_nop 0
	v_cvt_pk_bf16_f32 v31, v20, v21
	v_add_u32_e32 v20, 0xb0, v145
	v_lshrrev_b32_e32 v22, 3, v20
	v_lshlrev_b32_e32 v21, 6, v20
	v_and_or_b32 v22, v22, 14, s64
	v_lshlrev_b32_e32 v23, 2, v20
	v_and_or_b32 v21, v21, s15, v142
	v_lshlrev_b32_e32 v22, 10, v22
	v_and_b32_e32 v23, 32, v23
	v_bitop3_b32 v132, v21, v22, v23 bitop3:0xde
	v_mul_f32_e32 v22, 0xbfb8aa3b, v16
	v_mul_f32_e32 v23, 0xbfb8aa3b, v17
	v_exp_f32_e32 v22, v22
	v_exp_f32_e32 v23, v23
	v_lshlrev_b32_e32 v20, 7, v20
	v_and_b32_e32 v20, 0x4000, v20
	v_add_f32_e32 v22, 1.0, v22
	v_add_f32_e32 v23, 1.0, v23
	v_rcp_f32_e32 v22, v22
	v_rcp_f32_e32 v23, v23
	v_mov_b32_e32 v21, v133
	v_lshl_add_u64 v[20:21], v[68:69], 0, v[20:21]
	v_lshl_add_u64 v[20:21], v[20:21], 0, v[132:133]
	v_pk_mul_f32 v[16:17], v[16:17], v[22:23]
	global_store_dwordx4 v[36:37], v[28:31], off
	v_pk_mul_f32 v[12:13], v[16:17], v[12:13]
	s_nop 0
	v_cvt_pk_bf16_f32 v12, v12, v13
	v_mul_f32_e32 v13, 0xbfb8aa3b, v18
	v_exp_f32_e32 v13, v13
	s_nop 0
	v_add_f32_e32 v13, 1.0, v13
	v_rcp_f32_e32 v16, v13
	v_mul_f32_e32 v13, 0xbfb8aa3b, v19
	v_exp_f32_e32 v13, v13
	s_nop 0
	v_add_f32_e32 v13, 1.0, v13
	v_rcp_f32_e32 v17, v13
	s_nop 0
	v_pk_mul_f32 v[16:17], v[18:19], v[16:17]
	s_nop 0
	v_pk_mul_f32 v[14:15], v[16:17], v[14:15]
	s_nop 0
	v_cvt_pk_bf16_f32 v13, v14, v15
	v_mul_f32_e32 v14, 0xbfb8aa3b, v8
	v_mul_f32_e32 v15, 0xbfb8aa3b, v9
	v_exp_f32_e32 v14, v14
	v_exp_f32_e32 v15, v15
	v_add_f32_e32 v14, 1.0, v14
	v_add_f32_e32 v15, 1.0, v15
	v_rcp_f32_e32 v14, v14
	v_rcp_f32_e32 v15, v15
	s_nop 0
	v_pk_mul_f32 v[8:9], v[8:9], v[14:15]
	s_nop 0
	v_pk_mul_f32 v[4:5], v[8:9], v[4:5]
	s_nop 0
	v_cvt_pk_bf16_f32 v14, v4, v5
	v_mul_f32_e32 v4, 0xbfb8aa3b, v10
	v_mul_f32_e32 v5, 0xbfb8aa3b, v11
	v_exp_f32_e32 v4, v4
	v_exp_f32_e32 v5, v5
	v_add_f32_e32 v4, 1.0, v4
	v_add_f32_e32 v5, 1.0, v5
	v_rcp_f32_e32 v4, v4
	v_rcp_f32_e32 v5, v5
	s_nop 0
	v_pk_mul_f32 v[4:5], v[10:11], v[4:5]
	s_nop 0
	v_pk_mul_f32 v[4:5], v[4:5], v[6:7]
	s_nop 0
	v_cvt_pk_bf16_f32 v15, v4, v5
	global_store_dwordx4 v[20:21], v[12:15], off
	s_cbranch_vccz .LBB0_892
	s_waitcnt vmcnt(0)
	s_cmpk_gt_u32 s2, 0xff
	s_cbranch_scc1 .LBB0_903
	s_barrier
